# ret_out: QK blocks, PV loop and query x prefix-state k-steps read their LDS fragments up front with counted waits (were read/wait/MFMA per fragment)
# speedup vs baseline: 1.0015x; 1.0015x over previous
; DI float ex2(float x) { return __builtin_amdgcn_exp2f(x); }
; #define otid() otid_(wbase)
; DI void ret_out_unit(const Params& p, int hf, int bl, int c, int hd, unsigned char* shm, int tid, bool dry = false) {
;     ...
;   bf16_t* projb = (bf16_t*)(wsb + WS_PROJ) + (size_t)bl * SEQ * NP;
;   const float2* cs = (const float2*)(wsb + WS_CS) + (size_t)((hf * 2 + bl) * SEQ + c * 128) * 64;
;   const float lg = logf(1.0f - ex2(-5.0f - (float)hd));
; #pragma unroll
;   for (int it = 0; it < 2; ++it) {
;     const int idx = tid + it * NTHR, j = idx >> 3, dg = idx & 7;
;     const bf16_t* base = projb + (size_t)(c * 128 + j) * NP;
;     float q1[8], q2[8], k1[8], k2[8];
;     unpack8(*(const uint4*)(base + C_RQ + hd * 128 + dg * 8), q1); unpack8(*(const uint4*)(base + C_RQ + hd * 128 + 64 + dg * 8), q2);
;     unpack8(*(const uint4*)(base + C_RK + hd * 128 + dg * 8), k1); unpack8(*(const uint4*)(base + C_RK + hd * 128 + 64 + dg * 8), k2);
;     float oq1[8], oq2[8], ok1[8], ok2[8];
; #pragma unroll
;     for (int e = 0; e < 8; ++e) {
;       const float2 t = cs[j * 64 + dg * 8 + e];
;       oq1[e] = q1[e] * t.x - q2[e] * t.y; oq2[e] = q1[e] * t.y + q2[e] * t.x;
;       ok1[e] = (k1[e] * t.x - k2[e] * t.y) * 0.08838834764831845f; ok2[e] = (k1[e] * t.y + k2[e] * t.x) * 0.08838834764831845f;
;     }
;     *(uint4*)(sQ + j * LD + dg * 8) = pack8(oq1); *(uint4*)(sQ + j * LD + 64 + dg * 8) = pack8(oq2);
;     *(uint4*)(sK + j * LD + dg * 8) = pack8(ok1); *(uint4*)(sK + j * LD + 64 + dg * 8) = pack8(ok2);
;     *(uint4*)(sVt + j * LD + dg * 16) = *(const uint4*)(base + C_RV + hd * 128 + dg * 16);
;     *(uint4*)(sVt + j * LD + dg * 16 + 8) = *(const uint4*)(base + C_RV + hd * 128 + dg * 16 + 8);
; __global__ void __launch_bounds__(NTHR) mega(Params p) {
;     ...
;           if (u < 256) { fox_unit(p, hf, (u >> 3) & 1, u & 7, 31 - (u >> 4), shm, otid()); }
;           else if (u < 448) {
;             scan_unit(p, hf, u - 256, otid());
;             asm volatile("s_waitcnt vmcnt(0)" ::: "memory");
;             __syncthreads();
;             if (otid() == 0) { __builtin_amdgcn_fence(__ATOMIC_RELEASE, "agent"); asm volatile("s_waitcnt vmcnt(0)" ::: "memory"); __hip_atomic_fetch_add(dep, 1, __ATOMIC_RELAXED, __HIP_MEMORY_SCOPE_AGENT); }
;           }
;           else if (u < 576) { const int k = u - 448; ssd_out_unit(p, layer, hf, k >> 6, k & 63, shm, otid()); }
.LBB0_431:
	v_writelane_b32 v254, s4, 61
	s_nop 1
	v_writelane_b32 v254, s5, 62
	s_nop 0
	v_readlane_b32 s0, v254, 60
	s_cmpk_gt_i32 s0, 0xff
	s_mov_b64 s[0:1], -1
	s_cbranch_scc0 .LBB0_588
	v_readlane_b32 s0, v254, 60
	s_cmpk_gt_u32 s0, 0x1bf
	s_mov_b64 s[0:1], -1
	s_cbranch_scc0 .LBB0_573
	v_readlane_b32 s0, v254, 60
	s_cmpk_gt_i32 s0, 0x23f
	s_mov_b64 s[0:1], -1
	s_cbranch_scc0 .LBB0_500
	v_readlane_b32 s0, v254, 60
	s_cmpk_gt_u32 s0, 0x33f
	s_mov_b64 s[0:1], -1
	s_cbranch_scc0 .LBB0_468
	v_readlane_b32 s0, v254, 60
	s_add_i32 s5, s0, 0xfffffcc0
	s_lshr_b32 s4, s5, 8
	s_mul_i32 s2, s4, 0x3400000
	s_bfe_u32 s7, s5, 0x60002
	s_and_b32 s6, s23, 3
	s_lshl_b64 s[0:1], s[2:3], 1
	s_add_u32 s8, s38, s0
	v_cvt_f32_ubyte0_e32 v0, s6
	s_addc_u32 s9, s39, s1
	s_lshl_b32 s0, s4, 13
	v_sub_f32_e32 v0, 0xc0a00000, v0
	s_add_i32 s0, s0, s68
	s_lshl_b32 s4, s7, 7
	v_exp_f32_e32 v0, v0
	s_or_b32 s0, s0, s4
	s_lshl_b32 s2, s0, 6
	v_mov_b32_e32 v66, v163
	s_lshl_b64 s[0:1], s[2:3], 3
	v_readlane_b32 s2, v252, 45
	s_add_u32 s0, s2, s0
	v_readlane_b32 s2, v252, 46
	v_sub_f32_e32 v32, 1.0, v0
	v_and_b32_e32 v0, 7, v66
	v_ashrrev_i32_e32 v18, 3, v66
	s_addc_u32 s1, s2, s1
	v_lshlrev_b32_e32 v20, 3, v0
	v_lshlrev_b32_e32 v160, 4, v0
	v_lshlrev_b32_e32 v12, 5, v0
	v_readlane_b32 s2, v254, 0
	v_add_u32_e32 v0, s4, v18
	v_mov_b64_e32 v[16:17], s[8:9]
	v_add_u32_e32 v19, s2, v12
	v_mad_i64_i32 v[0:1], s[8:9], v0, s65, v[16:17]
	s_lshl_b32 s2, s6, 8
	v_lshl_add_u64 v[14:15], v[0:1], 0, s[2:3]
	v_lshl_add_u64 v[4:5], v[14:15], 0, v[160:161]
	v_lshl_add_u64 v[224:225], v[14:15], 0, v[160:161]
	global_load_dwordx4 v[100:103], v[224:225], off
	global_load_dwordx4 v[104:107], v[224:225], off offset:128
	global_load_dwordx4 v[108:111], v[224:225], off offset:1024
	global_load_dwordx4 v[112:115], v[224:225], off offset:1152
	v_lshl_or_b32 v226, v18, 6, v20
	v_mov_b32_e32 v227, v161
	v_lshl_add_u64 v[226:227], v[226:227], 3, s[0:1]
	global_load_dwordx4 v[116:119], v[226:227], off offset:48
	global_load_dwordx4 v[120:123], v[226:227], off offset:32
	global_load_dwordx4 v[124:127], v[226:227], off offset:16
	global_load_dwordx4 v[128:131], v[226:227], off
	v_mov_b32_e32 v228, v12
	v_mov_b32_e32 v229, v161
	v_lshl_add_u64 v[228:229], v[14:15], 0, v[228:229]
	global_load_dwordx4 v[132:135], v[228:229], off offset:2048
	global_load_dwordx4 v[136:139], v[228:229], off offset:2064
	v_add_u32_e32 v230, 64, v18
	v_add_u32_e32 v231, s4, v230
	v_mad_i64_i32 v[232:233], s[8:9], v231, s65, v[16:17]
	v_lshl_add_u64 v[232:233], v[232:233], 0, s[2:3]
	v_lshl_add_u64 v[234:235], v[232:233], 0, v[160:161]
	global_load_dwordx4 v[140:143], v[234:235], off
	global_load_dwordx4 v[144:147], v[234:235], off offset:128
	global_load_dwordx4 v[148:151], v[234:235], off offset:1024
	global_load_dwordx4 v[152:155], v[234:235], off offset:1152
	v_lshl_or_b32 v236, v230, 6, v20
	v_mov_b32_e32 v237, v161
	v_lshl_add_u64 v[236:237], v[236:237], 3, s[0:1]
	global_load_dwordx4 v[156:159], v[236:237], off offset:48
	global_load_dwordx4 v[204:207], v[236:237], off offset:32
	global_load_dwordx4 v[208:211], v[236:237], off offset:16
	global_load_dwordx4 v[212:215], v[236:237], off
	v_mov_b32_e32 v238, v12
	v_mov_b32_e32 v239, v161
	v_lshl_add_u64 v[238:239], v[232:233], 0, v[238:239]
	global_load_dwordx4 v[216:219], v[238:239], off offset:2048
	global_load_dwordx4 v[220:223], v[238:239], off offset:2064
	v_mul_lo_u32 v67, v18, s66
	v_ashrrev_i32_e32 v73, 6, v66
	v_and_b32_e32 v74, 15, v66
	v_lshl_or_b32 v68, v73, 4, v74
	v_bfe_u32 v75, v66, 4, 2
	v_mul_u32_u24_e32 v71, 0x110, v74
	s_waitcnt vmcnt(19)
	v_mov_b32_e32 v0, v100
	v_mov_b32_e32 v1, v101
	v_mov_b32_e32 v2, v102
	v_mov_b32_e32 v3, v103
	v_lshlrev_b32_e32 v26, 16, v0
	v_and_b32_e32 v27, 0xffff0000, v0
	v_lshlrev_b32_e32 v28, 16, v1
	v_and_b32_e32 v29, 0xffff0000, v1
	v_lshlrev_b32_e32 v30, 16, v2
	v_and_b32_e32 v31, 0xffff0000, v2
	v_lshlrev_b32_e32 v21, 16, v3
	v_and_b32_e32 v13, 0xffff0000, v3
	s_waitcnt vmcnt(18)
	v_mov_b32_e32 v0, v104
	v_mov_b32_e32 v1, v105
	v_mov_b32_e32 v2, v106
	v_mov_b32_e32 v3, v107
	v_lshlrev_b32_e32 v33, 16, v0
	v_and_b32_e32 v34, 0xffff0000, v0
	v_lshlrev_b32_e32 v35, 16, v1
	v_and_b32_e32 v36, 0xffff0000, v1
	v_lshlrev_b32_e32 v37, 16, v2
	v_and_b32_e32 v38, 0xffff0000, v2
	v_lshlrev_b32_e32 v39, 16, v3
	v_and_b32_e32 v40, 0xffff0000, v3
	s_waitcnt vmcnt(17)
	v_mov_b32_e32 v0, v108
	v_mov_b32_e32 v1, v109
	v_mov_b32_e32 v2, v110
	v_mov_b32_e32 v3, v111
	v_lshlrev_b32_e32 v41, 16, v0
	v_and_b32_e32 v42, 0xffff0000, v0
	v_lshlrev_b32_e32 v43, 16, v1
	v_and_b32_e32 v44, 0xffff0000, v1
	v_lshlrev_b32_e32 v45, 16, v2
	v_and_b32_e32 v46, 0xffff0000, v2
	v_lshlrev_b32_e32 v47, 16, v3
	v_and_b32_e32 v48, 0xffff0000, v3
	s_waitcnt vmcnt(16)
	v_mov_b32_e32 v0, v112
	v_mov_b32_e32 v1, v113
	v_mov_b32_e32 v2, v114
	v_mov_b32_e32 v3, v115
	v_lshlrev_b32_e32 v49, 16, v0
	v_and_b32_e32 v50, 0xffff0000, v0
	v_lshl_or_b32 v0, v18, 6, v20
	v_lshlrev_b32_e32 v51, 16, v1
	v_and_b32_e32 v52, 0xffff0000, v1
	v_ashrrev_i32_e32 v1, 31, v0
	v_lshl_add_u64 v[22:23], v[0:1], 3, s[0:1]
	v_lshlrev_b32_e32 v53, 16, v2
	v_and_b32_e32 v54, 0xffff0000, v2
	v_lshlrev_b32_e32 v55, 16, v3
	v_and_b32_e32 v56, 0xffff0000, v3
	s_nop 0
	s_waitcnt vmcnt(12)
; DI void unpack8(uint4 v, float* f) { f[0] = bflo(v.x); f[1] = bfhi(v.x); f[2] = bflo(v.y); f[3] = bfhi(v.y); f[4] = bflo(v.z); f[5] = bfhi(v.z); f[6] = bflo(v.w); f[7] = bfhi(v.w); }
; DI uint4 pack8(const float* f) { uint4 r; r.x = pk2(f[0], f[1]); r.y = pk2(f[2], f[3]); r.z = pk2(f[4], f[5]); r.w = pk2(f[6], f[7]); return r; }
; DI void ret_out_unit(const Params& p, int hf, int bl, int c, int hd, unsigned char* shm, int tid, bool dry = false) {
;     ...
;   for (int it = 0; it < 2; ++it) {
;     const int idx = tid + it * NTHR, j = idx >> 3, dg = idx & 7;
;     const bf16_t* base = projb + (size_t)(c * 128 + j) * NP;
;     float q1[8], q2[8], k1[8], k2[8];
;     unpack8(*(const uint4*)(base + C_RQ + hd * 128 + dg * 8), q1); unpack8(*(const uint4*)(base + C_RQ + hd * 128 + 64 + dg * 8), q2);
;     unpack8(*(const uint4*)(base + C_RK + hd * 128 + dg * 8), k1); unpack8(*(const uint4*)(base + C_RK + hd * 128 + 64 + dg * 8), k2);
;     float oq1[8], oq2[8], ok1[8], ok2[8];
; #pragma unroll
;     for (int e = 0; e < 8; ++e) {
;       const float2 t = cs[j * 64 + dg * 8 + e];
;       oq1[e] = q1[e] * t.x - q2[e] * t.y; oq2[e] = q1[e] * t.y + q2[e] * t.x;
;       ok1[e] = (k1[e] * t.x - k2[e] * t.y) * 0.08838834764831845f; ok2[e] = (k1[e] * t.y + k2[e] * t.x) * 0.08838834764831845f;
;     }
;     *(uint4*)(sQ + j * LD + dg * 8) = pack8(oq1); *(uint4*)(sQ + j * LD + 64 + dg * 8) = pack8(oq2);
;     *(uint4*)(sK + j * LD + dg * 8) = pack8(ok1); *(uint4*)(sK + j * LD + 64 + dg * 8) = pack8(ok2);
;     *(uint4*)(sVt + j * LD + dg * 16) = *(const uint4*)(base + C_RV + hd * 128 + dg * 16);
;     *(uint4*)(sVt + j * LD + dg * 16 + 8) = *(const uint4*)(base + C_RV + hd * 128 + dg * 16 + 8);
	v_mov_b32_e32 v0, v116
	v_mov_b32_e32 v1, v117
	v_mov_b32_e32 v2, v118
	v_mov_b32_e32 v3, v119
	v_mov_b32_e32 v4, v120
	v_mov_b32_e32 v5, v121
	v_mov_b32_e32 v6, v122
	v_mov_b32_e32 v7, v123
	v_mov_b32_e32 v8, v124
	v_mov_b32_e32 v9, v125
	v_mov_b32_e32 v10, v126
	v_mov_b32_e32 v11, v127
	v_mov_b32_e32 v22, v128
	v_mov_b32_e32 v23, v129
	v_mov_b32_e32 v24, v130
	v_mov_b32_e32 v25, v131
	v_mul_f32_e32 v57, v23, v33
	v_fma_f32 v57, v22, v26, -v57
	v_mul_f32_e32 v26, v23, v26
	v_fmac_f32_e32 v26, v22, v33
	v_mul_f32_e32 v33, v23, v49
	v_mul_f32_e32 v23, v23, v41
	v_fmac_f32_e32 v23, v22, v49
	v_fma_f32 v33, v22, v41, -v33
	v_mul_f32_e32 v22, 0x3db504f3, v23
	v_mul_f32_e32 v23, v25, v34
	v_fma_f32 v23, v24, v27, -v23
	v_mul_f32_e32 v27, v25, v27
	v_fmac_f32_e32 v27, v24, v34
	v_mul_f32_e32 v34, v25, v50
	v_mul_f32_e32 v25, v25, v42
	v_fmac_f32_e32 v25, v24, v50
	v_fma_f32 v34, v24, v42, -v34
	v_mul_f32_e32 v24, 0x3db504f3, v25
	v_mul_f32_e32 v25, v9, v35
	v_fma_f32 v25, v8, v28, -v25
	v_mul_f32_e32 v28, v9, v28
	v_fmac_f32_e32 v28, v8, v35
	v_mul_f32_e32 v35, v9, v51
	v_mul_f32_e32 v9, v9, v43
	v_fmac_f32_e32 v9, v8, v51
	v_fma_f32 v35, v8, v43, -v35
	v_mul_f32_e32 v8, 0x3db504f3, v9
	v_mul_f32_e32 v9, v11, v36
	v_fma_f32 v9, v10, v29, -v9
	v_mul_f32_e32 v29, v11, v29
	v_fmac_f32_e32 v29, v10, v36
	v_mul_f32_e32 v36, v11, v52
	v_mul_f32_e32 v11, v11, v44
	v_fmac_f32_e32 v11, v10, v52
	v_fma_f32 v36, v10, v44, -v36
	v_mul_f32_e32 v10, 0x3db504f3, v11
	v_mul_f32_e32 v11, v5, v37
	v_fma_f32 v11, v4, v30, -v11
	v_mul_f32_e32 v30, v5, v30
	v_fmac_f32_e32 v30, v4, v37
	v_mul_f32_e32 v37, v5, v53
	v_mul_f32_e32 v5, v5, v45
	v_fmac_f32_e32 v5, v4, v53
	v_fma_f32 v37, v4, v45, -v37
	v_mul_f32_e32 v4, 0x3db504f3, v5
	v_mul_f32_e32 v5, v7, v38
	v_fma_f32 v5, v6, v31, -v5
	v_mul_f32_e32 v31, v7, v31
	v_fmac_f32_e32 v31, v6, v38
	v_mul_f32_e32 v38, v7, v54
	v_mul_f32_e32 v7, v7, v46
	v_fmac_f32_e32 v7, v6, v54
	v_fma_f32 v38, v6, v46, -v38
	v_mul_f32_e32 v6, 0x3db504f3, v7
	v_mul_f32_e32 v7, v1, v39
	v_fma_f32 v7, v0, v21, -v7
	v_mul_f32_e32 v21, v1, v21
	v_fmac_f32_e32 v21, v0, v39
	v_mul_f32_e32 v39, v1, v55
	v_mul_f32_e32 v1, v1, v47
	v_fma_f32 v39, v0, v47, -v39
	v_fmac_f32_e32 v1, v0, v55
	v_mul_f32_e32 v0, v3, v40
	v_fma_f32 v42, v2, v13, -v0
	v_mul_f32_e32 v0, v3, v56
	v_mul_f32_e32 v13, v3, v13
	v_fma_f32 v0, v2, v48, -v0
	v_fmac_f32_e32 v13, v2, v40
	v_mul_f32_e32 v40, 0x3db504f3, v0
	v_mul_f32_e32 v0, v3, v48
	v_fmac_f32_e32 v0, v2, v56
	v_mul_f32_e32 v41, 0x3db504f3, v1
	v_mul_f32_e32 v43, 0x3db504f3, v0
	v_cvt_pk_bf16_f32 v0, v57, v23
	v_cvt_pk_bf16_f32 v1, v25, v9
	v_cvt_pk_bf16_f32 v2, v11, v5
	v_cvt_pk_bf16_f32 v3, v7, v42
	v_add3_u32 v5, 32, v67, v160
	ds_write_b128 v5, v[0:3]
	v_cvt_pk_bf16_f32 v0, v26, v27
	v_cvt_pk_bf16_f32 v1, v28, v29
	v_cvt_pk_bf16_f32 v2, v30, v31
	v_cvt_pk_bf16_f32 v3, v21, v13
	v_mul_f32_e32 v33, 0x3db504f3, v33
	v_mul_f32_e32 v34, 0x3db504f3, v34
	v_mul_f32_e32 v35, 0x3db504f3, v35
	v_mul_f32_e32 v36, 0x3db504f3, v36
	v_mul_f32_e32 v37, 0x3db504f3, v37
	v_mul_f32_e32 v38, 0x3db504f3, v38
	v_mul_f32_e32 v39, 0x3db504f3, v39
	ds_write_b128 v5, v[0:3] offset:128
	v_cvt_pk_bf16_f32 v0, v33, v34
	v_cvt_pk_bf16_f32 v1, v35, v36
	v_cvt_pk_bf16_f32 v2, v37, v38
	v_cvt_pk_bf16_f32 v3, v39, v40
	v_mov_b32_e32 v13, v161
	ds_write_b128 v5, v[0:3] offset:34816
	v_cvt_pk_bf16_f32 v0, v22, v24
	v_cvt_pk_bf16_f32 v1, v8, v10
	v_cvt_pk_bf16_f32 v2, v4, v6
	v_cvt_pk_bf16_f32 v3, v41, v43
	ds_write_b128 v5, v[0:3] offset:34944
	v_lshl_add_u64 v[4:5], v[14:15], 0, v[12:13]
	v_add_u32_e32 v6, v19, v67
	s_waitcnt vmcnt(11)
	v_mov_b32_e32 v0, v132
	v_mov_b32_e32 v1, v133
	v_mov_b32_e32 v2, v134
	v_mov_b32_e32 v3, v135
	ds_write_b128 v6, v[0:3]
	s_waitcnt vmcnt(10)
	v_mov_b32_e32 v0, v136
	v_mov_b32_e32 v1, v137
	v_mov_b32_e32 v2, v138
	v_mov_b32_e32 v3, v139
	ds_write_b128 v6, v[0:3] offset:16
	v_add_u32_e32 v0, 0x200, v66
	v_ashrrev_i32_e32 v14, 3, v0
	v_add_u32_e32 v0, s4, v14
	v_mad_i64_i32 v[0:1], s[8:9], v0, s65, v[16:17]
	v_lshl_add_u64 v[4:5], v[0:1], 0, s[2:3]
	v_lshl_add_u64 v[6:7], v[4:5], 0, v[160:161]
	v_lshl_add_u64 v[4:5], v[4:5], 0, v[12:13]
	s_waitcnt vmcnt(9)
	v_mov_b32_e32 v0, v140
	v_mov_b32_e32 v1, v141
	v_mov_b32_e32 v2, v142
	v_mov_b32_e32 v3, v143
	v_lshlrev_b32_e32 v15, 16, v0
	v_and_b32_e32 v28, 0xffff0000, v0
	v_lshlrev_b32_e32 v29, 16, v1
	v_and_b32_e32 v30, 0xffff0000, v1
	v_lshlrev_b32_e32 v31, 16, v2
	v_and_b32_e32 v33, 0xffff0000, v2
	v_lshlrev_b32_e32 v34, 16, v3
	v_and_b32_e32 v35, 0xffff0000, v3
	s_waitcnt vmcnt(8)
	v_mov_b32_e32 v0, v144
	v_mov_b32_e32 v1, v145
	v_mov_b32_e32 v2, v146
	v_mov_b32_e32 v3, v147
	v_lshlrev_b32_e32 v36, 16, v0
	v_and_b32_e32 v37, 0xffff0000, v0
	v_lshlrev_b32_e32 v38, 16, v1
	v_and_b32_e32 v39, 0xffff0000, v1
	v_lshlrev_b32_e32 v40, 16, v2
	v_and_b32_e32 v41, 0xffff0000, v2
	v_lshlrev_b32_e32 v42, 16, v3
	v_and_b32_e32 v43, 0xffff0000, v3
	s_waitcnt vmcnt(7)
	v_mov_b32_e32 v0, v148
	v_mov_b32_e32 v1, v149
	v_mov_b32_e32 v2, v150
	v_mov_b32_e32 v3, v151
	v_lshlrev_b32_e32 v44, 16, v0
	v_and_b32_e32 v45, 0xffff0000, v0
	v_lshlrev_b32_e32 v46, 16, v1
	v_and_b32_e32 v47, 0xffff0000, v1
	v_lshlrev_b32_e32 v48, 16, v2
	v_and_b32_e32 v49, 0xffff0000, v2
	v_lshlrev_b32_e32 v50, 16, v3
	v_and_b32_e32 v51, 0xffff0000, v3
	s_waitcnt vmcnt(6)
; DI void unpack8(uint4 v, float* f) { f[0] = bflo(v.x); f[1] = bfhi(v.x); f[2] = bflo(v.y); f[3] = bfhi(v.y); f[4] = bflo(v.z); f[5] = bfhi(v.z); f[6] = bflo(v.w); f[7] = bfhi(v.w); }
; DI uint4 pack8(const float* f) { uint4 r; r.x = pk2(f[0], f[1]); r.y = pk2(f[2], f[3]); r.z = pk2(f[4], f[5]); r.w = pk2(f[6], f[7]); return r; }
; DI void ret_out_unit(const Params& p, int hf, int bl, int c, int hd, unsigned char* shm, int tid, bool dry = false) {
;     ...
;   for (int it = 0; it < 2; ++it) {
;     const int idx = tid + it * NTHR, j = idx >> 3, dg = idx & 7;
;     const bf16_t* base = projb + (size_t)(c * 128 + j) * NP;
;     float q1[8], q2[8], k1[8], k2[8];
;     unpack8(*(const uint4*)(base + C_RQ + hd * 128 + dg * 8), q1); unpack8(*(const uint4*)(base + C_RQ + hd * 128 + 64 + dg * 8), q2);
;     unpack8(*(const uint4*)(base + C_RK + hd * 128 + dg * 8), k1); unpack8(*(const uint4*)(base + C_RK + hd * 128 + 64 + dg * 8), k2);
;     float oq1[8], oq2[8], ok1[8], ok2[8];
; #pragma unroll
;     for (int e = 0; e < 8; ++e) {
;       const float2 t = cs[j * 64 + dg * 8 + e];
;       oq1[e] = q1[e] * t.x - q2[e] * t.y; oq2[e] = q1[e] * t.y + q2[e] * t.x;
;       ok1[e] = (k1[e] * t.x - k2[e] * t.y) * 0.08838834764831845f; ok2[e] = (k1[e] * t.y + k2[e] * t.x) * 0.08838834764831845f;
;     }
;     *(uint4*)(sQ + j * LD + dg * 8) = pack8(oq1); *(uint4*)(sQ + j * LD + 64 + dg * 8) = pack8(oq2);
;     *(uint4*)(sK + j * LD + dg * 8) = pack8(ok1); *(uint4*)(sK + j * LD + 64 + dg * 8) = pack8(ok2);
;     *(uint4*)(sVt + j * LD + dg * 16) = *(const uint4*)(base + C_RV + hd * 128 + dg * 16);
;     *(uint4*)(sVt + j * LD + dg * 16 + 8) = *(const uint4*)(base + C_RV + hd * 128 + dg * 16 + 8);
;   }
;   __syncthreads();
;   const int wid = tid >> 6, lane = tid & 63, fr = lane & 15, fq = lane >> 4;
;   const int i_row = 16 * wid + fr;
;   uint4 stv0, stv1, stv2, stv3; uint2 gv8[8];
;   {
;     const bf16_t* st = (const bf16_t*)(wsb + WS_RST) + (size_t)((bl * 64 + c) * 4 + hd) * 16384;
;     { const int e0 = tid >> 3, dg = tid & 7; stv0 = *(const uint4*)(st + e0 * 128 + dg * 16); stv1 = *(const uint4*)(st + e0 * 128 + dg * 16 + 8); stv2 = *(const uint4*)(st + (e0 + 64) * 128 + dg * 16); stv3 = *(const uint4*)(st + (e0 + 64) * 128 + dg * 16 + 8); }
	v_mov_b32_e32 v0, v152
	v_mov_b32_e32 v1, v153
	v_mov_b32_e32 v2, v154
	v_mov_b32_e32 v3, v155
	v_lshlrev_b32_e32 v52, 16, v0
	v_and_b32_e32 v53, 0xffff0000, v0
	v_lshl_or_b32 v0, v14, 6, v20
	v_lshlrev_b32_e32 v54, 16, v1
	v_and_b32_e32 v55, 0xffff0000, v1
	v_ashrrev_i32_e32 v1, 31, v0
	v_lshl_add_u64 v[10:11], v[0:1], 3, s[0:1]
	v_lshlrev_b32_e32 v56, 16, v2
	v_and_b32_e32 v57, 0xffff0000, v2
	v_lshlrev_b32_e32 v58, 16, v3
	v_and_b32_e32 v59, 0xffff0000, v3
	s_and_b32 s0, s5, 0x3ff00
	s_lshl_b32 s1, s7, 2
	s_or_b32 s0, s1, s0
	s_or_b32 s0, s0, s6
	s_lshl_b32 s0, s0, 14
	s_mov_b32 s1, s3
	s_lshl_b64 s[0:1], s[0:1], 1
	v_readlane_b32 s5, v253, 28
	s_add_u32 s0, s5, s0
	v_readlane_b32 s5, v253, 29
	s_addc_u32 s1, s5, s1
	s_waitcnt vmcnt(2)
	v_mov_b32_e32 v0, v156
	v_mov_b32_e32 v1, v157
	v_mov_b32_e32 v2, v158
	v_mov_b32_e32 v3, v159
	v_mov_b32_e32 v6, v204
	v_mov_b32_e32 v7, v205
	v_mov_b32_e32 v8, v206
	v_mov_b32_e32 v9, v207
	v_mov_b32_e32 v20, v208
	v_mov_b32_e32 v21, v209
	v_mov_b32_e32 v22, v210
	v_mov_b32_e32 v23, v211
	v_mov_b32_e32 v24, v212
	v_mov_b32_e32 v25, v213
	v_mov_b32_e32 v26, v214
	v_mov_b32_e32 v27, v215
	v_mul_f32_e32 v10, v25, v36
	v_fma_f32 v10, v24, v15, -v10
	v_mul_f32_e32 v11, v25, v15
	v_mul_f32_e32 v15, v25, v52
	v_mul_f32_e32 v25, v25, v44
	v_fmac_f32_e32 v25, v24, v52
	v_fmac_f32_e32 v11, v24, v36
	v_fma_f32 v15, v24, v44, -v15
	v_mul_f32_e32 v24, 0x3db504f3, v25
	v_mul_f32_e32 v25, v27, v37
	v_fma_f32 v25, v26, v28, -v25
	v_mul_f32_e32 v28, v27, v28
	v_mul_f32_e32 v36, v27, v53
	v_mul_f32_e32 v27, v27, v45
	v_fmac_f32_e32 v27, v26, v53
	v_fmac_f32_e32 v28, v26, v37
	v_fma_f32 v36, v26, v45, -v36
	v_mul_f32_e32 v26, 0x3db504f3, v27
	v_mul_f32_e32 v27, v21, v38
	v_fma_f32 v27, v20, v29, -v27
	v_mul_f32_e32 v29, v21, v29
	v_mul_f32_e32 v37, v21, v54
	v_mul_f32_e32 v21, v21, v46
	v_fmac_f32_e32 v21, v20, v54
	v_fmac_f32_e32 v29, v20, v38
	v_fma_f32 v37, v20, v46, -v37
	v_mul_f32_e32 v20, 0x3db504f3, v21
	v_mul_f32_e32 v21, v23, v39
	v_fma_f32 v21, v22, v30, -v21
	v_mul_f32_e32 v30, v23, v30
	v_mul_f32_e32 v38, v23, v55
	v_mul_f32_e32 v23, v23, v47
	v_fmac_f32_e32 v23, v22, v55
	v_fmac_f32_e32 v30, v22, v39
	v_fma_f32 v38, v22, v47, -v38
	v_mul_f32_e32 v22, 0x3db504f3, v23
	v_mul_f32_e32 v23, v7, v40
	v_fma_f32 v23, v6, v31, -v23
	v_mul_f32_e32 v31, v7, v31
	v_mul_f32_e32 v39, v7, v56
	v_mul_f32_e32 v7, v7, v48
	v_fmac_f32_e32 v7, v6, v56
	v_fmac_f32_e32 v31, v6, v40
	v_fma_f32 v39, v6, v48, -v39
	v_mul_f32_e32 v6, 0x3db504f3, v7
	v_mul_f32_e32 v7, v9, v41
	v_fma_f32 v7, v8, v33, -v7
	v_mul_f32_e32 v33, v9, v33
	v_mul_f32_e32 v40, v9, v57
	v_mul_f32_e32 v9, v9, v49
	v_fmac_f32_e32 v9, v8, v57
	v_fmac_f32_e32 v33, v8, v41
	v_fma_f32 v40, v8, v49, -v40
	v_mul_f32_e32 v8, 0x3db504f3, v9
	v_mul_f32_e32 v9, v1, v42
	v_fma_f32 v9, v0, v34, -v9
	v_mul_f32_e32 v34, v1, v34
	v_mul_f32_e32 v41, v1, v58
	v_mul_f32_e32 v1, v1, v50
	v_fmac_f32_e32 v34, v0, v42
	v_fma_f32 v41, v0, v50, -v41
	v_fmac_f32_e32 v1, v0, v58
	v_mul_f32_e32 v0, v3, v43
	v_fma_f32 v44, v2, v35, -v0
	v_mul_f32_e32 v0, v3, v59
	v_mul_f32_e32 v35, v3, v35
	v_fma_f32 v0, v2, v51, -v0
	v_fmac_f32_e32 v35, v2, v43
	v_mul_f32_e32 v43, 0x3db504f3, v0
	v_mul_f32_e32 v0, v3, v51
	v_fmac_f32_e32 v0, v2, v59
	v_mul_f32_e32 v42, 0x3db504f3, v1
	v_mul_f32_e32 v45, 0x3db504f3, v0
	v_cvt_pk_bf16_f32 v0, v10, v25
	v_cvt_pk_bf16_f32 v1, v27, v21
	v_cvt_pk_bf16_f32 v2, v23, v7
	v_mul_lo_u32 v7, v14, s66
	v_cvt_pk_bf16_f32 v3, v9, v44
	v_add3_u32 v9, 32, v7, v160
	ds_write_b128 v9, v[0:3]
	v_cvt_pk_bf16_f32 v0, v11, v28
	v_cvt_pk_bf16_f32 v1, v29, v30
	v_cvt_pk_bf16_f32 v2, v31, v33
	v_cvt_pk_bf16_f32 v3, v34, v35
	v_mul_f32_e32 v15, 0x3db504f3, v15
	v_mul_f32_e32 v36, 0x3db504f3, v36
	v_mul_f32_e32 v37, 0x3db504f3, v37
	v_mul_f32_e32 v38, 0x3db504f3, v38
	v_mul_f32_e32 v39, 0x3db504f3, v39
	v_mul_f32_e32 v40, 0x3db504f3, v40
	v_mul_f32_e32 v41, 0x3db504f3, v41
	ds_write_b128 v9, v[0:3] offset:128
	v_cvt_pk_bf16_f32 v0, v15, v36
	v_cvt_pk_bf16_f32 v1, v37, v38
	v_cvt_pk_bf16_f32 v2, v39, v40
	v_cvt_pk_bf16_f32 v3, v41, v43
	ds_write_b128 v9, v[0:3] offset:34816
	v_cvt_pk_bf16_f32 v0, v24, v26
	v_cvt_pk_bf16_f32 v1, v20, v22
	v_cvt_pk_bf16_f32 v2, v6, v8
	v_cvt_pk_bf16_f32 v3, v42, v45
	ds_write_b128 v9, v[0:3] offset:34944
	v_add_u32_e32 v6, v19, v7
	v_lshlrev_b32_e32 v8, 7, v18
	v_ashrrev_i32_e32 v9, 31, v8
	v_add_u32_e32 v18, s4, v68
	v_lshlrev_b32_e32 v34, 3, v75
	v_mov_b32_e32 v35, v161
	v_mul_lo_u32 v33, v68, s66
	v_add_u32_e32 v70, 32, v33
	v_lshlrev_b32_e32 v36, 2, v75
	s_waitcnt vmcnt(1)
	v_mov_b32_e32 v0, v216
	v_mov_b32_e32 v1, v217
	v_mov_b32_e32 v2, v218
	v_mov_b32_e32 v3, v219
	ds_write_b128 v6, v[0:3]
	s_waitcnt vmcnt(0)
	v_mov_b32_e32 v0, v220
	v_mov_b32_e32 v1, v221
	v_mov_b32_e32 v2, v222
	v_mov_b32_e32 v3, v223
	ds_write_b128 v6, v[0:3] offset:16
	v_lshl_add_u64 v[0:1], v[8:9], 1, s[0:1]
	v_add_u32_e32 v8, 0x2000, v8
	v_ashrrev_i32_e32 v9, 31, v8
	v_lshl_add_u64 v[8:9], v[8:9], 1, s[0:1]
	v_mad_i64_i32 v[16:17], s[0:1], v18, s65, v[16:17]
	v_lshl_add_u64 v[16:17], v[16:17], 0, s[2:3]
	v_lshlrev_b32_e32 v2, 4, v66
	v_lshl_add_u64 v[16:17], v[16:17], 0, v[34:35]
	s_mov_b64 s[0:1], 0x2400
	v_and_b32_e32 v2, 0x70, v2
	v_lshl_add_u64 v[48:49], v[16:17], 0, s[0:1]
	s_movk_i32 s0, 0x2000
	v_lshlrev_b32_e32 v160, 1, v2
	v_add_co_u32_e32 v16, vcc, s0, v16
	v_lshl_add_u64 v[4:5], v[0:1], 0, v[160:161]
	v_lshl_add_u64 v[12:13], v[8:9], 0, v[160:161]
	v_addc_co_u32_e32 v17, vcc, 0, v17, vcc
	s_waitcnt lgkmcnt(0)
	s_barrier
; DI unsigned pk2(float lo, float hi) { unsigned r; asm volatile("v_cvt_pk_bf16_f32 %0, %1, %2" : "=v"(r) : "v"(lo), "v"(hi)); return r; }
; DI f32x4 mmaT(bf16x8 a_m, bf16x8 b_n, f32x4 c) { return __builtin_amdgcn_mfma_f32_16x16x32_bf16(b_n, a_m, c, 0, 0, 0); }
; DI void ret_out_unit(const Params& p, int hf, int bl, int c, int hd, unsigned char* shm, int tid, bool dry = false) {
;     ...
;   const int wid = tid >> 6, lane = tid & 63, fr = lane & 15, fq = lane >> 4;
;   const int i_row = 16 * wid + fr;
;   uint4 stv0, stv1, stv2, stv3; uint2 gv8[8];
;   {
;     const bf16_t* st = (const bf16_t*)(wsb + WS_RST) + (size_t)((bl * 64 + c) * 4 + hd) * 16384;
;     { const int e0 = tid >> 3, dg = tid & 7; stv0 = *(const uint4*)(st + e0 * 128 + dg * 16); stv1 = *(const uint4*)(st + e0 * 128 + dg * 16 + 8); stv2 = *(const uint4*)(st + (e0 + 64) * 128 + dg * 16); stv3 = *(const uint4*)(st + (e0 + 64) * 128 + dg * 16 + 8); }
;     const bf16_t* gp0 = projb + (size_t)(c * 128 + i_row) * NP + C_RG + hd * 128 + 4 * fq;
; #pragma unroll
;     for (int n = 0; n < 8; ++n) gv8[n] = *(const uint2*)(gp0 + 16 * n);
;   }
;   {
;     bf16x8 aq[4];
; #pragma unroll
;     for (int ks = 0; ks < 4; ++ks) aq[ks] = ldf(sQ, LD, 16 * wid, 32 * ks, fr, fq);
; #pragma unroll
;     for (int n = 0; n < 8; ++n) {
;       if (n <= (wid | 1)) {
;         uint2 w; w.x = 0u; w.y = 0u;
;         if (n <= wid) {
;           f32x4 s = (f32x4){0.f, 0.f, 0.f, 0.f};
; #pragma unroll
;           for (int ks = 0; ks < 4; ++ks) s = mmaT(aq[ks], ldf(sK, LD, 16 * n, 32 * ks, fr, fq), s);
;           float r[4];
; #pragma unroll
;           for (int j = 0; j < 4; ++j) { const int d = i_row - (16 * n + 4 * fq + j); r[j] = (d >= 0) ? s[j] * __expf(lg * (float)d) : 0.f; }
;           w.x = pk2(r[0], r[1]); w.y = pk2(r[2], r[3]);
;         }
;         *(uint2*)(sS + i_row * LD + 16 * n + 4 * fq) = w;
;       }
;     }
	global_load_dwordx4 v[0:3], v[4:5], off offset:16
	s_nop 0
	global_load_dwordx4 v[4:7], v[4:5], off
	s_nop 0
	global_load_dwordx4 v[8:11], v[12:13], off offset:16
	s_nop 0
	global_load_dwordx4 v[12:15], v[12:13], off
	s_nop 0
	global_load_dwordx2 v[64:65], v[16:17], off offset:1024
	global_load_dwordx2 v[62:63], v[48:49], off offset:32
	global_load_dwordx2 v[60:61], v[48:49], off offset:64
	global_load_dwordx2 v[58:59], v[48:49], off offset:96
	global_load_dwordx2 v[56:57], v[48:49], off offset:128
	global_load_dwordx2 v[54:55], v[48:49], off offset:160
	global_load_dwordx2 v[52:53], v[48:49], off offset:192
	global_load_dwordx2 v[50:51], v[48:49], off offset:224
	s_mov_b32 s0, 0x800000
	v_cmp_gt_f32_e32 vcc, s0, v32
	s_and_b64 s[0:1], vcc, exec
	s_cselect_b32 s0, 32, 0
	v_ldexp_f32 v32, v32, s0
	v_log_f32_e32 v32, v32
	v_and_b32_e32 v35, 48, v66
	v_add_u32_e32 v16, v70, v35
	ds_read_b128 v[28:31], v16
	ds_read_b128 v[24:27], v16 offset:64
	ds_read_b128 v[20:23], v16 offset:128
	ds_read_b128 v[16:19], v16 offset:192
	v_mul_f32_e32 v37, 0x3f317217, v32
	s_mov_b32 s0, 0x3f317217
	v_fma_f32 v37, v32, s0, -v37
	v_fmac_f32_e32 v37, 0x3377d1cf, v32
	s_mov_b32 s0, 0x7f800000
	v_fmac_f32_e32 v37, 0x3f317217, v32
	v_cmp_lt_f32_e64 s[0:1], |v32|, s0
	v_add_u32_e32 v38, 32, v35
	s_nop 0
	v_cndmask_b32_e64 v32, v32, v37, s[0:1]
	v_cndmask_b32_e32 v37, 0, v201, vcc
	v_readlane_b32 s0, v254, 1
	v_sub_f32_e32 v69, v32, v37
	v_cmp_lt_i32_e32 vcc, -1, v73
	v_add3_u32 v37, s0, v33, v34
	s_and_saveexec_b64 s[0:1], vcc
	s_cbranch_execz .LBB0_439
	v_mad_u32_u24 v39, v74, s66, v38
	ds_read_b128 v[32:35], v39 offset:34816
	ds_read_b128 v[40:43], v39 offset:34880
	ds_read_b128 v[240:243], v39 offset:34944
	ds_read_b128 v[244:247], v39 offset:35008
	s_waitcnt lgkmcnt(3)
	v_mfma_f32_16x16x32_bf16 v[32:35], v[32:35], v[28:31], 0
	s_waitcnt lgkmcnt(2)
	v_mfma_f32_16x16x32_bf16 v[32:35], v[40:43], v[24:27], v[32:35]
	s_waitcnt lgkmcnt(1)
	v_mfma_f32_16x16x32_bf16 v[32:35], v[240:243], v[20:23], v[32:35]
	v_sub_u32_e32 v39, v68, v36
	v_cmp_lt_i32_e32 vcc, -1, v39
	v_cvt_f32_u32_e32 v39, v39
	s_waitcnt lgkmcnt(0)
	v_mfma_f32_16x16x32_bf16 v[32:35], v[244:247], v[16:19], v[32:35]
	v_mul_f32_e32 v39, v69, v39
	v_mul_f32_e32 v39, 0x3fb8aa3b, v39
	v_exp_f32_e32 v39, v39
	s_nop 4
	v_mul_f32_e32 v32, v39, v32
	v_xad_u32 v39, v36, -1, v68
	v_cndmask_b32_e32 v32, 0, v32, vcc
	v_cmp_lt_i32_e32 vcc, -1, v39
	v_cvt_f32_u32_e32 v39, v39
	v_mul_f32_e32 v39, v69, v39
	v_mul_f32_e32 v39, 0x3fb8aa3b, v39
	v_exp_f32_e32 v39, v39
	s_nop 0
	v_mul_f32_e32 v33, v39, v33
	v_or_b32_e32 v39, 2, v36
	v_sub_u32_e32 v39, v68, v39
	v_cndmask_b32_e32 v33, 0, v33, vcc
	v_cmp_lt_i32_e32 vcc, -1, v39
	v_cvt_f32_u32_e32 v39, v39
	v_cvt_pk_bf16_f32 v32, v32, v33
	v_mul_f32_e32 v39, v69, v39
	v_mul_f32_e32 v39, 0x3fb8aa3b, v39
	v_exp_f32_e32 v39, v39
	s_nop 0
	v_mul_f32_e32 v34, v39, v34
	v_or_b32_e32 v39, 3, v36
	v_sub_u32_e32 v39, v68, v39
	v_cndmask_b32_e32 v34, 0, v34, vcc
	v_cmp_lt_i32_e32 vcc, -1, v39
	v_cvt_f32_u32_e32 v39, v39
	v_mul_f32_e32 v39, v69, v39
	v_mul_f32_e32 v39, 0x3fb8aa3b, v39
	v_exp_f32_e32 v39, v39
	s_nop 0
	v_mul_f32_e32 v35, v39, v35
	v_cndmask_b32_e32 v35, 0, v35, vcc
	v_cvt_pk_bf16_f32 v33, v34, v35
	ds_write_b64 v37, v[32:33]
	v_cmp_lt_u32_e32 vcc, 63, v66
	v_mov_b32_e32 v32, 0
	v_mov_b32_e32 v33, 0
	s_and_saveexec_b64 s[4:5], vcc
	s_cbranch_execz .LBB0_438
	v_add_u32_e32 v39, v38, v71
	ds_read_b128 v[32:35], v39 offset:39168
	ds_read_b128 v[40:43], v39 offset:39232
	ds_read_b128 v[240:243], v39 offset:39296
	ds_read_b128 v[244:247], v39 offset:39360
	s_waitcnt lgkmcnt(3)
	v_mfma_f32_16x16x32_bf16 v[32:35], v[32:35], v[28:31], 0
	s_waitcnt lgkmcnt(2)
	v_mfma_f32_16x16x32_bf16 v[32:35], v[40:43], v[24:27], v[32:35]
	s_waitcnt lgkmcnt(1)
	v_mfma_f32_16x16x32_bf16 v[32:35], v[240:243], v[20:23], v[32:35]
	v_or_b32_e32 v39, 16, v36
	v_sub_u32_e32 v39, v68, v39
	v_cmp_lt_i32_e32 vcc, -1, v39
	v_cvt_f32_u32_e32 v39, v39
	s_waitcnt lgkmcnt(0)
	v_mfma_f32_16x16x32_bf16 v[32:35], v[244:247], v[16:19], v[32:35]
	v_mul_f32_e32 v39, v69, v39
	v_mul_f32_e32 v39, 0x3fb8aa3b, v39
	v_exp_f32_e32 v39, v39
	s_nop 4
	v_mul_f32_e32 v32, v39, v32
	v_or_b32_e32 v39, 17, v36
	v_sub_u32_e32 v39, v68, v39
	v_cndmask_b32_e32 v32, 0, v32, vcc
	v_cmp_lt_i32_e32 vcc, -1, v39
	v_cvt_f32_u32_e32 v39, v39
	v_mul_f32_e32 v39, v69, v39
	v_mul_f32_e32 v39, 0x3fb8aa3b, v39
	v_exp_f32_e32 v39, v39
	s_nop 0
	v_mul_f32_e32 v33, v39, v33
	v_or_b32_e32 v39, 18, v36
	v_sub_u32_e32 v39, v68, v39
	v_cndmask_b32_e32 v33, 0, v33, vcc
	v_cmp_lt_i32_e32 vcc, -1, v39
	v_cvt_f32_u32_e32 v39, v39
	v_cvt_pk_bf16_f32 v32, v32, v33
	v_mul_f32_e32 v39, v69, v39
	v_mul_f32_e32 v39, 0x3fb8aa3b, v39
	v_exp_f32_e32 v39, v39
	s_nop 0
	v_mul_f32_e32 v34, v39, v34
	v_or_b32_e32 v39, 19, v36
	v_sub_u32_e32 v39, v68, v39
	v_cndmask_b32_e32 v34, 0, v34, vcc
	v_cmp_lt_i32_e32 vcc, -1, v39
	v_cvt_f32_u32_e32 v39, v39
	v_mul_f32_e32 v39, v69, v39
	v_mul_f32_e32 v39, 0x3fb8aa3b, v39
	v_exp_f32_e32 v39, v39
	s_nop 0
	v_mul_f32_e32 v35, v39, v35
	v_cndmask_b32_e32 v35, 0, v35, vcc
	v_cvt_pk_bf16_f32 v33, v34, v35

; DI unsigned pk2(float lo, float hi) { unsigned r; asm volatile("v_cvt_pk_bf16_f32 %0, %1, %2" : "=v"(r) : "v"(lo), "v"(hi)); return r; }
; DI f32x4 mmaT(bf16x8 a_m, bf16x8 b_n, f32x4 c) { return __builtin_amdgcn_mfma_f32_16x16x32_bf16(b_n, a_m, c, 0, 0, 0); }
; DI void ret_out_unit(const Params& p, int hf, int bl, int c, int hd, unsigned char* shm, int tid, bool dry = false) {
;     ...
;     for (int n = 0; n < 8; ++n) {
;       if (n <= (wid | 1)) {
;         uint2 w; w.x = 0u; w.y = 0u;
;         if (n <= wid) {
;           f32x4 s = (f32x4){0.f, 0.f, 0.f, 0.f};
; #pragma unroll
;           for (int ks = 0; ks < 4; ++ks) s = mmaT(aq[ks], ldf(sK, LD, 16 * n, 32 * ks, fr, fq), s);
;           float r[4];
; #pragma unroll
;           for (int j = 0; j < 4; ++j) { const int d = i_row - (16 * n + 4 * fq + j); r[j] = (d >= 0) ? s[j] * __expf(lg * (float)d) : 0.f; }
;           w.x = pk2(r[0], r[1]); w.y = pk2(r[2], r[3]);
;         }
;         *(uint2*)(sS + i_row * LD + 16 * n + 4 * fq) = w;
;       }
;     }
.LBB0_445:
	v_cmp_lt_i32_e32 vcc, 1, v73
	v_mov_b32_e32 v32, 0
	v_mov_b32_e32 v33, 0
	s_and_saveexec_b64 s[4:5], vcc
	s_cbranch_execz .LBB0_447
	v_mad_u32_u24 v44, v74, s66, v38
	ds_read_b128 v[32:35], v44 offset:43520
	ds_read_b128 v[40:43], v44 offset:43584
	ds_read_b128 v[240:243], v44 offset:43648
	ds_read_b128 v[244:247], v44 offset:43712
	s_waitcnt lgkmcnt(3)
	v_mfma_f32_16x16x32_bf16 v[32:35], v[32:35], v[28:31], 0
	s_waitcnt lgkmcnt(2)
	v_mfma_f32_16x16x32_bf16 v[32:35], v[40:43], v[24:27], v[32:35]
	s_waitcnt lgkmcnt(1)
	v_mfma_f32_16x16x32_bf16 v[32:35], v[240:243], v[20:23], v[32:35]
	s_waitcnt lgkmcnt(0)
	v_mfma_f32_16x16x32_bf16 v[32:35], v[244:247], v[16:19], v[32:35]
	v_or_b32_e32 v40, 32, v36
	v_sub_u32_e32 v40, v68, v40
	v_cmp_lt_i32_e32 vcc, -1, v40
	v_cvt_f32_u32_e32 v40, v40
	v_mul_f32_e32 v40, v69, v40
	v_mul_f32_e32 v40, 0x3fb8aa3b, v40
	v_exp_f32_e32 v40, v40
	s_nop 0
	v_mul_f32_e32 v32, v40, v32
	v_or_b32_e32 v40, 33, v36
	v_sub_u32_e32 v40, v68, v40
	v_cndmask_b32_e32 v32, 0, v32, vcc
	v_cmp_lt_i32_e32 vcc, -1, v40
	v_cvt_f32_u32_e32 v40, v40
	v_mul_f32_e32 v40, v69, v40
	v_mul_f32_e32 v40, 0x3fb8aa3b, v40
	v_exp_f32_e32 v40, v40
	s_nop 0
	v_mul_f32_e32 v33, v40, v33
	v_or_b32_e32 v40, 34, v36
	v_sub_u32_e32 v40, v68, v40
	v_cndmask_b32_e32 v33, 0, v33, vcc
	v_cmp_lt_i32_e32 vcc, -1, v40
	v_cvt_f32_u32_e32 v40, v40
	v_cvt_pk_bf16_f32 v32, v32, v33
	v_mul_f32_e32 v40, v69, v40
	v_mul_f32_e32 v40, 0x3fb8aa3b, v40
	v_exp_f32_e32 v40, v40
	s_nop 0
	v_mul_f32_e32 v34, v40, v34
	v_or_b32_e32 v40, 35, v36
	v_sub_u32_e32 v40, v68, v40
	v_cndmask_b32_e32 v34, 0, v34, vcc
	v_cmp_lt_i32_e32 vcc, -1, v40
	v_cvt_f32_u32_e32 v40, v40
	v_mul_f32_e32 v40, v69, v40
	v_mul_f32_e32 v40, 0x3fb8aa3b, v40
	v_exp_f32_e32 v40, v40
	s_nop 0
	v_mul_f32_e32 v35, v40, v35
	v_cndmask_b32_e32 v35, 0, v35, vcc
	v_cvt_pk_bf16_f32 v33, v34, v35

; DI unsigned pk2(float lo, float hi) { unsigned r; asm volatile("v_cvt_pk_bf16_f32 %0, %1, %2" : "=v"(r) : "v"(lo), "v"(hi)); return r; }
; DI f32x4 mmaT(bf16x8 a_m, bf16x8 b_n, f32x4 c) { return __builtin_amdgcn_mfma_f32_16x16x32_bf16(b_n, a_m, c, 0, 0, 0); }
; DI void ret_out_unit(const Params& p, int hf, int bl, int c, int hd, unsigned char* shm, int tid, bool dry = false) {
;     ...
;     for (int n = 0; n < 8; ++n) {
;       if (n <= (wid | 1)) {
;         uint2 w; w.x = 0u; w.y = 0u;
;         if (n <= wid) {
;           f32x4 s = (f32x4){0.f, 0.f, 0.f, 0.f};
; #pragma unroll
;           for (int ks = 0; ks < 4; ++ks) s = mmaT(aq[ks], ldf(sK, LD, 16 * n, 32 * ks, fr, fq), s);
;           float r[4];
; #pragma unroll
;           for (int j = 0; j < 4; ++j) { const int d = i_row - (16 * n + 4 * fq + j); r[j] = (d >= 0) ? s[j] * __expf(lg * (float)d) : 0.f; }
;           w.x = pk2(r[0], r[1]); w.y = pk2(r[2], r[3]);
;         }
;         *(uint2*)(sS + i_row * LD + 16 * n + 4 * fq) = w;
;       }
;     }
.LBB0_448:
	v_cmp_lt_i32_e32 vcc, 2, v73
	v_mov_b32_e32 v32, 0
	v_mov_b32_e32 v33, 0
	s_and_saveexec_b64 s[4:5], vcc
	s_cbranch_execz .LBB0_450
	v_mad_u32_u24 v44, v74, s66, v38
	ds_read_b128 v[32:35], v44 offset:47872
	ds_read_b128 v[40:43], v44 offset:47936
	ds_read_b128 v[240:243], v44 offset:48000
	ds_read_b128 v[244:247], v44 offset:48064
	s_waitcnt lgkmcnt(3)
	v_mfma_f32_16x16x32_bf16 v[32:35], v[32:35], v[28:31], 0
	s_waitcnt lgkmcnt(2)
	v_mfma_f32_16x16x32_bf16 v[32:35], v[40:43], v[24:27], v[32:35]
	s_waitcnt lgkmcnt(1)
	v_mfma_f32_16x16x32_bf16 v[32:35], v[240:243], v[20:23], v[32:35]
	s_waitcnt lgkmcnt(0)
	v_mfma_f32_16x16x32_bf16 v[32:35], v[244:247], v[16:19], v[32:35]
	v_or_b32_e32 v40, 48, v36
	v_sub_u32_e32 v40, v68, v40
	v_cmp_lt_i32_e32 vcc, -1, v40
	v_cvt_f32_u32_e32 v40, v40
	v_mul_f32_e32 v40, v69, v40
	v_mul_f32_e32 v40, 0x3fb8aa3b, v40
	v_exp_f32_e32 v40, v40
	s_nop 0
	v_mul_f32_e32 v32, v40, v32
	v_or_b32_e32 v40, 49, v36
	v_sub_u32_e32 v40, v68, v40
	v_cndmask_b32_e32 v32, 0, v32, vcc
	v_cmp_lt_i32_e32 vcc, -1, v40
	v_cvt_f32_u32_e32 v40, v40
	v_mul_f32_e32 v40, v69, v40
	v_mul_f32_e32 v40, 0x3fb8aa3b, v40
	v_exp_f32_e32 v40, v40
	s_nop 0
	v_mul_f32_e32 v33, v40, v33
	v_or_b32_e32 v40, 50, v36
	v_sub_u32_e32 v40, v68, v40
	v_cndmask_b32_e32 v33, 0, v33, vcc
	v_cmp_lt_i32_e32 vcc, -1, v40
	v_cvt_f32_u32_e32 v40, v40
	v_cvt_pk_bf16_f32 v32, v32, v33
	v_mul_f32_e32 v40, v69, v40
	v_mul_f32_e32 v40, 0x3fb8aa3b, v40
	v_exp_f32_e32 v40, v40
	s_nop 0
	v_mul_f32_e32 v34, v40, v34
	v_or_b32_e32 v40, 51, v36
	v_sub_u32_e32 v40, v68, v40
	v_cndmask_b32_e32 v34, 0, v34, vcc
	v_cmp_lt_i32_e32 vcc, -1, v40
	v_cvt_f32_u32_e32 v40, v40
	v_mul_f32_e32 v40, v69, v40
	v_mul_f32_e32 v40, 0x3fb8aa3b, v40
	v_exp_f32_e32 v40, v40
	s_nop 0
	v_mul_f32_e32 v35, v40, v35
	v_cndmask_b32_e32 v35, 0, v35, vcc
	v_cvt_pk_bf16_f32 v33, v34, v35

; DI unsigned pk2(float lo, float hi) { unsigned r; asm volatile("v_cvt_pk_bf16_f32 %0, %1, %2" : "=v"(r) : "v"(lo), "v"(hi)); return r; }
; DI f32x4 mmaT(bf16x8 a_m, bf16x8 b_n, f32x4 c) { return __builtin_amdgcn_mfma_f32_16x16x32_bf16(b_n, a_m, c, 0, 0, 0); }
; DI void ret_out_unit(const Params& p, int hf, int bl, int c, int hd, unsigned char* shm, int tid, bool dry = false) {
;     ...
;     for (int n = 0; n < 8; ++n) {
;       if (n <= (wid | 1)) {
;         uint2 w; w.x = 0u; w.y = 0u;
;         if (n <= wid) {
;           f32x4 s = (f32x4){0.f, 0.f, 0.f, 0.f};
; #pragma unroll
;           for (int ks = 0; ks < 4; ++ks) s = mmaT(aq[ks], ldf(sK, LD, 16 * n, 32 * ks, fr, fq), s);
;           float r[4];
; #pragma unroll
;           for (int j = 0; j < 4; ++j) { const int d = i_row - (16 * n + 4 * fq + j); r[j] = (d >= 0) ? s[j] * __expf(lg * (float)d) : 0.f; }
;           w.x = pk2(r[0], r[1]); w.y = pk2(r[2], r[3]);
;         }
;         *(uint2*)(sS + i_row * LD + 16 * n + 4 * fq) = w;
;       }
;     }
.LBB0_451:
	v_cmp_lt_i32_e32 vcc, 3, v73
	v_mov_b32_e32 v32, 0
	v_mov_b32_e32 v33, 0
	s_and_saveexec_b64 s[4:5], vcc
	s_cbranch_execz .LBB0_453
	v_mad_u32_u24 v44, v74, s66, v38
	ds_read_b128 v[32:35], v44 offset:52224
	ds_read_b128 v[40:43], v44 offset:52288
	ds_read_b128 v[240:243], v44 offset:52352
	ds_read_b128 v[244:247], v44 offset:52416
	s_waitcnt lgkmcnt(3)
	v_mfma_f32_16x16x32_bf16 v[32:35], v[32:35], v[28:31], 0
	s_waitcnt lgkmcnt(2)
	v_mfma_f32_16x16x32_bf16 v[32:35], v[40:43], v[24:27], v[32:35]
	s_waitcnt lgkmcnt(1)
	v_mfma_f32_16x16x32_bf16 v[32:35], v[240:243], v[20:23], v[32:35]
	s_waitcnt lgkmcnt(0)
	v_mfma_f32_16x16x32_bf16 v[32:35], v[244:247], v[16:19], v[32:35]
	v_or_b32_e32 v40, 64, v36
	v_sub_u32_e32 v40, v68, v40
	v_cmp_lt_i32_e32 vcc, -1, v40
	v_cvt_f32_u32_e32 v40, v40
	v_mul_f32_e32 v40, v69, v40
	v_mul_f32_e32 v40, 0x3fb8aa3b, v40
	v_exp_f32_e32 v40, v40
	s_nop 0
	v_mul_f32_e32 v32, v40, v32
	v_or_b32_e32 v40, 0x41, v36
	v_sub_u32_e32 v40, v68, v40
	v_cndmask_b32_e32 v32, 0, v32, vcc
	v_cmp_lt_i32_e32 vcc, -1, v40
	v_cvt_f32_u32_e32 v40, v40
	v_mul_f32_e32 v40, v69, v40
	v_mul_f32_e32 v40, 0x3fb8aa3b, v40
	v_exp_f32_e32 v40, v40
	s_nop 0
	v_mul_f32_e32 v33, v40, v33
	v_or_b32_e32 v40, 0x42, v36
	v_sub_u32_e32 v40, v68, v40
	v_cndmask_b32_e32 v33, 0, v33, vcc
	v_cmp_lt_i32_e32 vcc, -1, v40
	v_cvt_f32_u32_e32 v40, v40
	v_cvt_pk_bf16_f32 v32, v32, v33
	v_mul_f32_e32 v40, v69, v40
	v_mul_f32_e32 v40, 0x3fb8aa3b, v40
	v_exp_f32_e32 v40, v40
	s_nop 0
	v_mul_f32_e32 v34, v40, v34
	v_or_b32_e32 v40, 0x43, v36
	v_sub_u32_e32 v40, v68, v40
	v_cndmask_b32_e32 v34, 0, v34, vcc
	v_cmp_lt_i32_e32 vcc, -1, v40
	v_cvt_f32_u32_e32 v40, v40
	v_mul_f32_e32 v40, v69, v40
	v_mul_f32_e32 v40, 0x3fb8aa3b, v40
	v_exp_f32_e32 v40, v40
	s_nop 0
	v_mul_f32_e32 v35, v40, v35
	v_cndmask_b32_e32 v35, 0, v35, vcc
	v_cvt_pk_bf16_f32 v33, v34, v35

; DI unsigned pk2(float lo, float hi) { unsigned r; asm volatile("v_cvt_pk_bf16_f32 %0, %1, %2" : "=v"(r) : "v"(lo), "v"(hi)); return r; }
; DI f32x4 mmaT(bf16x8 a_m, bf16x8 b_n, f32x4 c) { return __builtin_amdgcn_mfma_f32_16x16x32_bf16(b_n, a_m, c, 0, 0, 0); }
; DI void ret_out_unit(const Params& p, int hf, int bl, int c, int hd, unsigned char* shm, int tid, bool dry = false) {
;     ...
;     for (int n = 0; n < 8; ++n) {
;       if (n <= (wid | 1)) {
;         uint2 w; w.x = 0u; w.y = 0u;
;         if (n <= wid) {
;           f32x4 s = (f32x4){0.f, 0.f, 0.f, 0.f};
; #pragma unroll
;           for (int ks = 0; ks < 4; ++ks) s = mmaT(aq[ks], ldf(sK, LD, 16 * n, 32 * ks, fr, fq), s);
;           float r[4];
; #pragma unroll
;           for (int j = 0; j < 4; ++j) { const int d = i_row - (16 * n + 4 * fq + j); r[j] = (d >= 0) ? s[j] * __expf(lg * (float)d) : 0.f; }
;           w.x = pk2(r[0], r[1]); w.y = pk2(r[2], r[3]);
;         }
;         *(uint2*)(sS + i_row * LD + 16 * n + 4 * fq) = w;
;       }
;     }
.LBB0_454:
	v_cmp_lt_i32_e32 vcc, 4, v73
	v_mov_b32_e32 v32, 0
	v_mov_b32_e32 v33, 0
	s_and_saveexec_b64 s[4:5], vcc
	s_cbranch_execz .LBB0_456
	v_mad_u32_u24 v44, v74, s66, v38
	ds_read_b128 v[32:35], v44 offset:56576
	ds_read_b128 v[40:43], v44 offset:56640
	ds_read_b128 v[240:243], v44 offset:56704
	ds_read_b128 v[244:247], v44 offset:56768
	s_waitcnt lgkmcnt(3)
	v_mfma_f32_16x16x32_bf16 v[32:35], v[32:35], v[28:31], 0
	s_waitcnt lgkmcnt(2)
	v_mfma_f32_16x16x32_bf16 v[32:35], v[40:43], v[24:27], v[32:35]
	s_waitcnt lgkmcnt(1)
	v_mfma_f32_16x16x32_bf16 v[32:35], v[240:243], v[20:23], v[32:35]
	s_waitcnt lgkmcnt(0)
	v_mfma_f32_16x16x32_bf16 v[32:35], v[244:247], v[16:19], v[32:35]
	v_or_b32_e32 v40, 0x50, v36
	v_sub_u32_e32 v40, v68, v40
	v_cmp_lt_i32_e32 vcc, -1, v40
	v_cvt_f32_u32_e32 v40, v40
	v_mul_f32_e32 v40, v69, v40
	v_mul_f32_e32 v40, 0x3fb8aa3b, v40
	v_exp_f32_e32 v40, v40
	s_nop 0
	v_mul_f32_e32 v32, v40, v32
	v_or_b32_e32 v40, 0x51, v36
	v_sub_u32_e32 v40, v68, v40
	v_cndmask_b32_e32 v32, 0, v32, vcc
	v_cmp_lt_i32_e32 vcc, -1, v40
	v_cvt_f32_u32_e32 v40, v40
	v_mul_f32_e32 v40, v69, v40
	v_mul_f32_e32 v40, 0x3fb8aa3b, v40
	v_exp_f32_e32 v40, v40
	s_nop 0
	v_mul_f32_e32 v33, v40, v33
	v_or_b32_e32 v40, 0x52, v36
	v_sub_u32_e32 v40, v68, v40
	v_cndmask_b32_e32 v33, 0, v33, vcc
	v_cmp_lt_i32_e32 vcc, -1, v40
	v_cvt_f32_u32_e32 v40, v40
	v_cvt_pk_bf16_f32 v32, v32, v33
	v_mul_f32_e32 v40, v69, v40
	v_mul_f32_e32 v40, 0x3fb8aa3b, v40
	v_exp_f32_e32 v40, v40
	s_nop 0
	v_mul_f32_e32 v34, v40, v34
	v_or_b32_e32 v40, 0x53, v36
	v_sub_u32_e32 v40, v68, v40
	v_cndmask_b32_e32 v34, 0, v34, vcc
	v_cmp_lt_i32_e32 vcc, -1, v40
	v_cvt_f32_u32_e32 v40, v40
	v_mul_f32_e32 v40, v69, v40
	v_mul_f32_e32 v40, 0x3fb8aa3b, v40
	v_exp_f32_e32 v40, v40
	s_nop 0
	v_mul_f32_e32 v35, v40, v35
	v_cndmask_b32_e32 v35, 0, v35, vcc
	v_cvt_pk_bf16_f32 v33, v34, v35

; DI unsigned pk2(float lo, float hi) { unsigned r; asm volatile("v_cvt_pk_bf16_f32 %0, %1, %2" : "=v"(r) : "v"(lo), "v"(hi)); return r; }
; DI f32x4 mmaT(bf16x8 a_m, bf16x8 b_n, f32x4 c) { return __builtin_amdgcn_mfma_f32_16x16x32_bf16(b_n, a_m, c, 0, 0, 0); }
; DI void ret_out_unit(const Params& p, int hf, int bl, int c, int hd, unsigned char* shm, int tid, bool dry = false) {
;     ...
;     for (int n = 0; n < 8; ++n) {
;       if (n <= (wid | 1)) {
;         uint2 w; w.x = 0u; w.y = 0u;
;         if (n <= wid) {
;           f32x4 s = (f32x4){0.f, 0.f, 0.f, 0.f};
; #pragma unroll
;           for (int ks = 0; ks < 4; ++ks) s = mmaT(aq[ks], ldf(sK, LD, 16 * n, 32 * ks, fr, fq), s);
;           float r[4];
; #pragma unroll
;           for (int j = 0; j < 4; ++j) { const int d = i_row - (16 * n + 4 * fq + j); r[j] = (d >= 0) ? s[j] * __expf(lg * (float)d) : 0.f; }
;           w.x = pk2(r[0], r[1]); w.y = pk2(r[2], r[3]);
;         }
;         *(uint2*)(sS + i_row * LD + 16 * n + 4 * fq) = w;
;       }
;     }
.LBB0_457:
	v_cmp_lt_i32_e32 vcc, 5, v73
	v_mov_b32_e32 v32, 0
	v_mov_b32_e32 v33, 0
	s_and_saveexec_b64 s[4:5], vcc
	s_cbranch_execz .LBB0_459
	v_mad_u32_u24 v44, v74, s66, v38
	ds_read_b128 v[32:35], v44 offset:60928
	ds_read_b128 v[40:43], v44 offset:60992
	ds_read_b128 v[240:243], v44 offset:61056
	ds_read_b128 v[244:247], v44 offset:61120
	s_waitcnt lgkmcnt(3)
	v_mfma_f32_16x16x32_bf16 v[32:35], v[32:35], v[28:31], 0
	s_waitcnt lgkmcnt(2)
	v_mfma_f32_16x16x32_bf16 v[32:35], v[40:43], v[24:27], v[32:35]
	s_waitcnt lgkmcnt(1)
	v_mfma_f32_16x16x32_bf16 v[32:35], v[240:243], v[20:23], v[32:35]
	s_waitcnt lgkmcnt(0)
	v_mfma_f32_16x16x32_bf16 v[32:35], v[244:247], v[16:19], v[32:35]
	v_or_b32_e32 v40, 0x60, v36
	v_sub_u32_e32 v40, v68, v40
	v_cmp_lt_i32_e32 vcc, -1, v40
	v_cvt_f32_u32_e32 v40, v40
	v_mul_f32_e32 v40, v69, v40
	v_mul_f32_e32 v40, 0x3fb8aa3b, v40
	v_exp_f32_e32 v40, v40
	s_nop 0
	v_mul_f32_e32 v32, v40, v32
	v_or_b32_e32 v40, 0x61, v36
	v_sub_u32_e32 v40, v68, v40
	v_cndmask_b32_e32 v32, 0, v32, vcc
	v_cmp_lt_i32_e32 vcc, -1, v40
	v_cvt_f32_u32_e32 v40, v40
	v_mul_f32_e32 v40, v69, v40
	v_mul_f32_e32 v40, 0x3fb8aa3b, v40
	v_exp_f32_e32 v40, v40
	s_nop 0
	v_mul_f32_e32 v33, v40, v33
	v_or_b32_e32 v40, 0x62, v36
	v_sub_u32_e32 v40, v68, v40
	v_cndmask_b32_e32 v33, 0, v33, vcc
	v_cmp_lt_i32_e32 vcc, -1, v40
	v_cvt_f32_u32_e32 v40, v40
	v_cvt_pk_bf16_f32 v32, v32, v33
	v_mul_f32_e32 v40, v69, v40
	v_mul_f32_e32 v40, 0x3fb8aa3b, v40
	v_exp_f32_e32 v40, v40
	s_nop 0
	v_mul_f32_e32 v34, v40, v34
	v_or_b32_e32 v40, 0x63, v36
	v_sub_u32_e32 v40, v68, v40
	v_cndmask_b32_e32 v34, 0, v34, vcc
	v_cmp_lt_i32_e32 vcc, -1, v40
	v_cvt_f32_u32_e32 v40, v40
	v_mul_f32_e32 v40, v69, v40
	v_mul_f32_e32 v40, 0x3fb8aa3b, v40
	v_exp_f32_e32 v40, v40
	s_nop 0
	v_mul_f32_e32 v35, v40, v35
	v_cndmask_b32_e32 v35, 0, v35, vcc
	v_cvt_pk_bf16_f32 v33, v34, v35

; DI f32x4 mmaT(bf16x8 a_m, bf16x8 b_n, f32x4 c) { return __builtin_amdgcn_mfma_f32_16x16x32_bf16(b_n, a_m, c, 0, 0, 0); }
; DI void ret_out_unit(const Params& p, int hf, int bl, int c, int hd, unsigned char* shm, int tid, bool dry = false) {
;     ...
;   const int nks = (wid >> 1) + 1;
;   for (int ks = 0; ks < nks; ++ks) {
;     const bf16x8 a = ldf(sS, LD, 16 * wid, 32 * ks, fr, fq);
; #pragma unroll
;     for (int n = 0; n < 8; ++n) o1[n] = mmaT(a, frag_tr(sVt, LD, 32 * ks, 16 * n, fr, fq), o1[n]);
;   }
;   __syncthreads();
;   {
;     { const int e0 = tid >> 3, dg = tid & 7;
;       *(uint4*)(sK + e0 * LD + dg * 16) = stv0; *(uint4*)(sK + e0 * LD + dg * 16 + 8) = stv1;
;       *(uint4*)(sK + (e0 + 64) * LD + dg * 16) = stv2; *(uint4*)(sK + (e0 + 64) * LD + dg * 16 + 8) = stv3; }
;   }
;   __syncthreads();
;   f32x4 o2[8];
; #pragma unroll
;   for (int n = 0; n < 8; ++n) o2[n] = (f32x4){0.f, 0.f, 0.f, 0.f};
; #pragma unroll
;   for (int ks = 0; ks < 4; ++ks) {
;     const bf16x8 a = ldf(sQ, LD, 16 * wid, 32 * ks, fr, fq);
; #pragma unroll
;     for (int n = 0; n < 8; ++n) o2[n] = mmaT(a, ldf(sK, LD, 16 * n, 32 * ks, fr, fq), o2[n]);
;   }
.LBB0_465:
	v_add_u32_e32 v74, 32, v73
	ds_read_b128 v[78:81], v74
	v_add_u32_e32 v74, 32, v66
	v_add_u32_e32 v75, 0x11000, v74
	ds_read_b64_tr_b16 v[172:173], v75
	ds_read_b64_tr_b16 v[174:175], v75 offset:1088
	ds_read_b64_tr_b16 v[176:177], v75 offset:32
	ds_read_b64_tr_b16 v[178:179], v75 offset:1120
	ds_read_b64_tr_b16 v[180:181], v75 offset:64
	ds_read_b64_tr_b16 v[182:183], v75 offset:1152
	ds_read_b64_tr_b16 v[184:185], v75 offset:96
	ds_read_b64_tr_b16 v[186:187], v75 offset:1184
	ds_read_b64_tr_b16 v[188:189], v75 offset:128
	ds_read_b64_tr_b16 v[190:191], v75 offset:1216
	ds_read_b64_tr_b16 v[240:241], v75 offset:160
	ds_read_b64_tr_b16 v[242:243], v75 offset:1248
	ds_read_b64_tr_b16 v[244:245], v75 offset:192
	ds_read_b64_tr_b16 v[246:247], v75 offset:1280
	ds_read_b64_tr_b16 v[248:249], v75 offset:224
	ds_read_b64_tr_b16 v[250:251], v75 offset:1312
	v_add_u32_e32 v77, -1, v77
	v_cmp_eq_u32_e32 vcc, 0, v77
	v_add_u32_e32 v66, 0x2200, v66
	v_add_u32_e32 v73, 64, v73
	s_or_b64 s[4:5], vcc, s[4:5]
	s_waitcnt lgkmcnt(14)
	v_mfma_f32_16x16x32_bf16 v[36:39], v[172:175], v[78:81], v[36:39]
	s_waitcnt lgkmcnt(12)
	v_mfma_f32_16x16x32_bf16 v[32:35], v[176:179], v[78:81], v[32:35]
	s_waitcnt lgkmcnt(10)
	v_mfma_f32_16x16x32_bf16 v[28:31], v[180:183], v[78:81], v[28:31]
	s_waitcnt lgkmcnt(8)
	v_mfma_f32_16x16x32_bf16 v[24:27], v[184:187], v[78:81], v[24:27]
	s_waitcnt lgkmcnt(6)
	v_mfma_f32_16x16x32_bf16 v[20:23], v[188:191], v[78:81], v[20:23]
	s_waitcnt lgkmcnt(4)
	v_mfma_f32_16x16x32_bf16 v[16:19], v[240:243], v[78:81], v[16:19]
	s_waitcnt lgkmcnt(2)
	v_mfma_f32_16x16x32_bf16 v[44:47], v[244:247], v[78:81], v[44:47]
	s_waitcnt lgkmcnt(0)
	v_mfma_f32_16x16x32_bf16 v[40:43], v[248:251], v[78:81], v[40:43]
	s_andn2_b64 exec, exec, s[4:5]
	s_cbranch_execnz .LBB0_465
	s_or_b64 exec, exec, s[4:5]
.LBB0_467:
	s_or_b64 exec, exec, s[0:1]
	v_add3_u32 v66, 32, v67, v160
	s_barrier
	s_waitcnt vmcnt(10)
	ds_write_b128 v66, v[4:7] offset:34816
	ds_write_b128 v66, v[0:3] offset:34832
	s_waitcnt vmcnt(8)
	ds_write_b128 v66, v[12:15] offset:52224
	ds_write_b128 v66, v[8:11] offset:52240
	v_add_u32_e32 v66, v70, v76
	v_add3_u32 v67, 32, v76, v71
	s_waitcnt lgkmcnt(0)
	s_barrier
	ds_read_b128 v[0:3], v66
	ds_read_b128 v[4:7], v67 offset:34816
	ds_read_b128 v[8:11], v67 offset:39168
	ds_read_b128 v[12:15], v67 offset:43520
	ds_read_b128 v[74:77], v67 offset:47872
	ds_read_b128 v[78:81], v67 offset:52224
	ds_read_b128 v[82:85], v67 offset:56576
	ds_read_b128 v[86:89], v67 offset:60928
	ds_read_b128 v[90:93], v67 offset:65280
	s_waitcnt lgkmcnt(7)
	v_mfma_f32_16x16x32_bf16 v[4:7], v[4:7], v[0:3], 0
	s_mov_b32 s0, 0x800000
	s_waitcnt lgkmcnt(6)
	v_mfma_f32_16x16x32_bf16 v[8:11], v[8:11], v[0:3], 0
	s_waitcnt lgkmcnt(5)
	v_mfma_f32_16x16x32_bf16 v[12:15], v[12:15], v[0:3], 0
	s_waitcnt lgkmcnt(4)
	v_mfma_f32_16x16x32_bf16 v[74:77], v[74:77], v[0:3], 0
	s_waitcnt lgkmcnt(3)
	v_mfma_f32_16x16x32_bf16 v[78:81], v[78:81], v[0:3], 0
	s_waitcnt lgkmcnt(2)
	v_mfma_f32_16x16x32_bf16 v[82:85], v[82:85], v[0:3], 0
	s_waitcnt lgkmcnt(1)
	v_mfma_f32_16x16x32_bf16 v[86:89], v[86:89], v[0:3], 0
	s_waitcnt lgkmcnt(0)
	v_mfma_f32_16x16x32_bf16 v[0:3], v[90:93], v[0:3], 0
	ds_read_b128 v[90:93], v66 offset:64
	ds_read_b128 v[172:175], v67 offset:34880
	ds_read_b128 v[176:179], v67 offset:39232
	ds_read_b128 v[180:183], v67 offset:43584
	ds_read_b128 v[184:187], v67 offset:47936
	ds_read_b128 v[188:191], v67 offset:52288
	ds_read_b128 v[240:243], v67 offset:56640
	ds_read_b128 v[244:247], v67 offset:60992
	ds_read_b128 v[248:251], v67 offset:65344
	s_waitcnt lgkmcnt(7)
	v_mfma_f32_16x16x32_bf16 v[4:7], v[172:175], v[90:93], v[4:7]
	s_waitcnt lgkmcnt(6)
	v_mfma_f32_16x16x32_bf16 v[8:11], v[176:179], v[90:93], v[8:11]
	s_waitcnt lgkmcnt(5)
	v_mfma_f32_16x16x32_bf16 v[12:15], v[180:183], v[90:93], v[12:15]
	s_waitcnt lgkmcnt(4)
	v_mfma_f32_16x16x32_bf16 v[74:77], v[184:187], v[90:93], v[74:77]
	s_waitcnt lgkmcnt(3)
	v_mfma_f32_16x16x32_bf16 v[78:81], v[188:191], v[90:93], v[78:81]
	s_waitcnt lgkmcnt(2)
	v_mfma_f32_16x16x32_bf16 v[82:85], v[240:243], v[90:93], v[82:85]
	s_waitcnt lgkmcnt(1)
	v_mfma_f32_16x16x32_bf16 v[86:89], v[244:247], v[90:93], v[86:89]
	s_waitcnt lgkmcnt(0)
	v_mfma_f32_16x16x32_bf16 v[0:3], v[248:251], v[90:93], v[0:3]
	ds_read_b128 v[90:93], v66 offset:128
	ds_read_b128 v[172:175], v67 offset:34944
	ds_read_b128 v[176:179], v67 offset:39296
	ds_read_b128 v[180:183], v67 offset:43648
	ds_read_b128 v[184:187], v67 offset:48000
	ds_read_b128 v[188:191], v67 offset:52352
	ds_read_b128 v[240:243], v67 offset:56704
	ds_read_b128 v[244:247], v67 offset:61056
	ds_read_b128 v[248:251], v67 offset:65408
	s_waitcnt lgkmcnt(7)
	v_mfma_f32_16x16x32_bf16 v[4:7], v[172:175], v[90:93], v[4:7]
	s_waitcnt lgkmcnt(6)
	v_mfma_f32_16x16x32_bf16 v[8:11], v[176:179], v[90:93], v[8:11]
	s_waitcnt lgkmcnt(5)
	v_mfma_f32_16x16x32_bf16 v[12:15], v[180:183], v[90:93], v[12:15]
	s_waitcnt lgkmcnt(4)
	v_mfma_f32_16x16x32_bf16 v[74:77], v[184:187], v[90:93], v[74:77]
	s_waitcnt lgkmcnt(3)
	v_mfma_f32_16x16x32_bf16 v[78:81], v[188:191], v[90:93], v[78:81]
	s_waitcnt lgkmcnt(2)
	v_mfma_f32_16x16x32_bf16 v[82:85], v[240:243], v[90:93], v[82:85]
	s_waitcnt lgkmcnt(1)
	v_mfma_f32_16x16x32_bf16 v[86:89], v[244:247], v[90:93], v[86:89]
	s_waitcnt lgkmcnt(0)
	v_mfma_f32_16x16x32_bf16 v[0:3], v[248:251], v[90:93], v[0:3]
	ds_read_b128 v[90:93], v66 offset:192
	ds_read_b128 v[172:175], v67 offset:35008
	ds_read_b128 v[176:179], v67 offset:39360
	ds_read_b128 v[180:183], v67 offset:43712
	ds_read_b128 v[184:187], v67 offset:48064
	ds_read_b128 v[188:191], v67 offset:52416
	ds_read_b128 v[240:243], v67 offset:56768
	ds_read_b128 v[244:247], v67 offset:61120
	ds_read_b128 v[248:251], v67 offset:65472
	s_waitcnt lgkmcnt(7)
; DI unsigned pk2(float lo, float hi) { unsigned r; asm volatile("v_cvt_pk_bf16_f32 %0, %1, %2" : "=v"(r) : "v"(lo), "v"(hi)); return r; }
; DI float bflo(unsigned u) { return __uint_as_float(u << 16); }
; DI float bfhi(unsigned u) { return __uint_as_float(u & 0xffff0000u); }
; DI float silu_f(float x) { return x * __builtin_amdgcn_rcpf(1.0f + __expf(-x)); }
; DI f32x4 mmaT(bf16x8 a_m, bf16x8 b_n, f32x4 c) { return __builtin_amdgcn_mfma_f32_16x16x32_bf16(b_n, a_m, c, 0, 0, 0); }
; DI float shx(float v, int m, int lane) { return __int_as_float(__builtin_amdgcn_ds_bpermute((lane ^ m) << 2, __float_as_int(v))); }
; DI void ret_out_unit(const Params& p, int hf, int bl, int c, int hd, unsigned char* shm, int tid, bool dry = false) {
;     ...
; #pragma unroll
;   for (int ks = 0; ks < 4; ++ks) {
;     const bf16x8 a = ldf(sQ, LD, 16 * wid, 32 * ks, fr, fq);
; #pragma unroll
;     for (int n = 0; n < 8; ++n) o2[n] = mmaT(a, ldf(sK, LD, 16 * n, 32 * ks, fr, fq), o2[n]);
;   }
;   const float dq = __expf(lg * (float)(i_row + 1));
;   float ss = 0.f;
; #pragma unroll
;   for (int n = 0; n < 8; ++n)
; #pragma unroll
;     for (int j = 0; j < 4; ++j) { const float v = o1[n][j] + o2[n][j] * dq; o1[n][j] = v; ss += v * v; }
;   ss += shx(ss, 16, lane); ss += shx(ss, 32, lane);
;   const float rinv = rsqrtf(ss * (1.0f / 128.0f) + EPS);
;   bf16_t* gp = projb + (size_t)(c * 128 + i_row) * NP + C_RG + hd * 128 + 4 * fq;
; #pragma unroll
;   for (int n = 0; n < 8; ++n) {
;     const uint2 gv = gv8[n];
;     uint2 w;
;     w.x = pk2(o1[n][0] * rinv * silu_f(bflo(gv.x)), o1[n][1] * rinv * silu_f(bfhi(gv.x)));
;     w.y = pk2(o1[n][2] * rinv * silu_f(bflo(gv.y)), o1[n][3] * rinv * silu_f(bfhi(gv.y)));
;     if (!dry || rinv == 1.2345e-30f) *(uint2*)(gp + 16 * n) = w;
;   }
	v_mfma_f32_16x16x32_bf16 v[4:7], v[172:175], v[90:93], v[4:7]
	s_waitcnt lgkmcnt(6)
	v_mfma_f32_16x16x32_bf16 v[8:11], v[176:179], v[90:93], v[8:11]
	s_waitcnt lgkmcnt(5)
	v_mfma_f32_16x16x32_bf16 v[12:15], v[180:183], v[90:93], v[12:15]
	s_waitcnt lgkmcnt(4)
	v_mfma_f32_16x16x32_bf16 v[74:77], v[184:187], v[90:93], v[74:77]
	s_waitcnt lgkmcnt(3)
	v_mfma_f32_16x16x32_bf16 v[78:81], v[188:191], v[90:93], v[78:81]
	s_waitcnt lgkmcnt(2)
	v_mfma_f32_16x16x32_bf16 v[82:85], v[240:243], v[90:93], v[82:85]
	s_waitcnt lgkmcnt(1)
	v_mfma_f32_16x16x32_bf16 v[86:89], v[244:247], v[90:93], v[86:89]
	s_waitcnt lgkmcnt(0)
	v_mfma_f32_16x16x32_bf16 v[90:93], v[248:251], v[90:93], v[0:3]
	s_nop 2
	v_add_u32_e32 v0, 1, v68
	v_cvt_f32_i32_e32 v0, v0
	v_mul_f32_e32 v0, v69, v0
	v_mul_f32_e32 v0, 0x3fb8aa3b, v0
	v_exp_f32_e32 v0, v0
	s_nop 0
	v_fmac_f32_e32 v37, v0, v5
	v_fmac_f32_e32 v36, v0, v4
	v_mul_f32_e32 v1, v37, v37
	v_fmac_f32_e32 v1, v36, v36
	v_fmac_f32_e32 v38, v0, v6
	v_fmac_f32_e32 v1, v38, v38
	v_fmac_f32_e32 v39, v0, v7
	v_fmac_f32_e32 v1, v39, v39
	v_fmac_f32_e32 v32, v0, v8
	v_fmac_f32_e32 v1, v32, v32
	v_fmac_f32_e32 v33, v0, v9
	v_fmac_f32_e32 v1, v33, v33
	v_fmac_f32_e32 v34, v0, v10
	v_fmac_f32_e32 v1, v34, v34
	v_fmac_f32_e32 v35, v0, v11
	v_fmac_f32_e32 v1, v35, v35
	v_fmac_f32_e32 v28, v0, v12
	v_fmac_f32_e32 v1, v28, v28
	v_fmac_f32_e32 v29, v0, v13
	v_fmac_f32_e32 v1, v29, v29
	v_fmac_f32_e32 v30, v0, v14
	v_fmac_f32_e32 v1, v30, v30
	v_fmac_f32_e32 v31, v0, v15
	v_fmac_f32_e32 v1, v31, v31
	v_fmac_f32_e32 v24, v0, v74
	v_fmac_f32_e32 v1, v24, v24
	v_fmac_f32_e32 v25, v0, v75
	v_fmac_f32_e32 v1, v25, v25
	v_fmac_f32_e32 v26, v0, v76
	v_fmac_f32_e32 v1, v26, v26
	v_fmac_f32_e32 v27, v0, v77
	v_fmac_f32_e32 v1, v27, v27
	v_fmac_f32_e32 v20, v0, v78
	v_fmac_f32_e32 v1, v20, v20
	v_fmac_f32_e32 v21, v0, v79
	v_fmac_f32_e32 v1, v21, v21
	v_fmac_f32_e32 v22, v0, v80
	v_fmac_f32_e32 v1, v22, v22
	v_fmac_f32_e32 v23, v0, v81
	v_fmac_f32_e32 v1, v23, v23
	v_fmac_f32_e32 v16, v0, v82
	v_fmac_f32_e32 v1, v16, v16
	v_fmac_f32_e32 v17, v0, v83
	v_fmac_f32_e32 v1, v17, v17
	v_fmac_f32_e32 v18, v0, v84
	v_fmac_f32_e32 v1, v18, v18
	v_fmac_f32_e32 v19, v0, v85
	v_fmac_f32_e32 v1, v19, v19
	v_pk_fma_f32 v[6:7], v[0:1], v[86:87], v[44:45] op_sel_hi:[0,1,1]
	v_pk_mul_f32 v[2:3], v[6:7], v[6:7]
	s_nop 0
	v_add_f32_e32 v1, v2, v1
	v_add_f32_e32 v1, v3, v1
	v_pk_fma_f32 v[4:5], v[0:1], v[88:89], v[46:47] op_sel_hi:[0,1,1]
	v_pk_mul_f32 v[2:3], v[4:5], v[4:5]
	s_nop 0
	v_add_f32_e32 v1, v2, v1
	v_add_f32_e32 v1, v3, v1
	v_pk_fma_f32 v[2:3], v[0:1], v[90:91], v[40:41] op_sel_hi:[0,1,1]
	v_pk_mul_f32 v[8:9], v[2:3], v[2:3]
	s_nop 0
	v_add_f32_e32 v1, v8, v1
	v_add_f32_e32 v10, v9, v1
	v_pk_fma_f32 v[0:1], v[0:1], v[92:93], v[42:43] op_sel_hi:[0,1,1]
	v_pk_mul_f32 v[8:9], v[0:1], v[0:1]
	s_nop 0
	v_add_f32_e32 v8, v8, v10
	v_add_f32_e32 v8, v9, v8
	v_lshlrev_b32_e32 v9, 2, v72
	v_xor_b32_e32 v10, 64, v9
	ds_bpermute_b32 v10, v10, v8
	v_xor_b32_e32 v9, 0x80, v9
	s_waitcnt lgkmcnt(0)
	v_add_f32_e32 v8, v8, v10
	s_waitcnt vmcnt(7)
	v_lshlrev_b32_e32 v10, 16, v64
	v_mul_f32_e32 v11, 0xbfb8aa3b, v10
	v_exp_f32_e32 v11, v11
	ds_bpermute_b32 v9, v9, v8
	v_add_f32_e32 v11, 1.0, v11
	v_rcp_f32_e32 v11, v11
	s_waitcnt lgkmcnt(0)
	v_add_f32_e32 v8, v8, v9
	v_fmamk_f32 v8, v8, 0x3c000000, v162
	v_cmp_gt_f32_e32 vcc, s0, v8
	v_mul_f32_e32 v10, v11, v10
	v_and_b32_e32 v11, 0xffff0000, v64
	v_mul_f32_e32 v12, 0xbfb8aa3b, v11
	v_mul_f32_e32 v9, 0x4b800000, v8
	v_exp_f32_e32 v12, v12
	v_cndmask_b32_e32 v8, v8, v9, vcc
	v_rsq_f32_e32 v8, v8
	s_mov_b64 s[0:1], 0
	v_add_f32_e32 v12, 1.0, v12
	v_rcp_f32_e32 v12, v12
	v_mul_f32_e32 v9, 0x45800000, v8
	v_cndmask_b32_e32 v8, v8, v9, vcc
	v_mul_f32_e32 v9, v36, v8
	v_mul_f32_e32 v9, v10, v9
	v_mul_f32_e32 v10, v37, v8
	v_mul_f32_e32 v11, v12, v11
	v_mul_f32_e32 v10, v11, v10
	v_lshlrev_b32_e32 v11, 16, v65
	v_mul_f32_e32 v12, 0xbfb8aa3b, v11
	v_exp_f32_e32 v12, v12
	v_cvt_pk_bf16_f32 v10, v9, v10
	v_mul_f32_e32 v9, v38, v8
	v_mul_f32_e32 v6, v6, v8
	v_add_f32_e32 v12, 1.0, v12
	v_rcp_f32_e32 v12, v12
	v_mul_f32_e32 v7, v7, v8
	v_mul_f32_e32 v4, v4, v8
	v_mul_f32_e32 v5, v5, v8
	v_mul_f32_e32 v11, v12, v11
	v_and_b32_e32 v12, 0xffff0000, v65
	v_mul_f32_e32 v13, 0xbfb8aa3b, v12
	v_exp_f32_e32 v13, v13
	v_mul_f32_e32 v9, v11, v9
	v_mul_f32_e32 v11, v39, v8
	v_mul_f32_e32 v2, v2, v8
	v_add_f32_e32 v13, 1.0, v13
	v_rcp_f32_e32 v13, v13
	v_mul_f32_e32 v3, v3, v8
	v_mul_f32_e32 v0, v0, v8
	v_mul_f32_e32 v1, v1, v8
	v_mul_f32_e32 v12, v13, v12
	v_mul_f32_e32 v11, v12, v11
	v_cvt_pk_bf16_f32 v11, v9, v11
	global_store_dwordx2 v[48:49], v[10:11], off
	s_waitcnt vmcnt(7)
	v_lshlrev_b32_e32 v10, 16, v62
	v_mul_f32_e32 v11, 0xbfb8aa3b, v10
	v_exp_f32_e32 v11, v11
	v_mul_f32_e32 v9, v32, v8
	v_add_f32_e32 v11, 1.0, v11
	v_rcp_f32_e32 v11, v11
	s_nop 0
	v_mul_f32_e32 v10, v11, v10
	v_and_b32_e32 v11, 0xffff0000, v62
	v_mul_f32_e32 v12, 0xbfb8aa3b, v11
	v_exp_f32_e32 v12, v12
	v_mul_f32_e32 v9, v10, v9
	v_mul_f32_e32 v10, v33, v8
	v_add_f32_e32 v12, 1.0, v12
	v_rcp_f32_e32 v12, v12
	s_nop 0
	v_mul_f32_e32 v11, v12, v11
	v_mul_f32_e32 v10, v11, v10
	v_lshlrev_b32_e32 v11, 16, v63
	v_mul_f32_e32 v12, 0xbfb8aa3b, v11
	v_exp_f32_e32 v12, v12
	v_cvt_pk_bf16_f32 v10, v9, v10
	v_mul_f32_e32 v9, v34, v8
	v_add_f32_e32 v12, 1.0, v12
	v_rcp_f32_e32 v12, v12
	s_nop 0
	v_mul_f32_e32 v11, v12, v11
	v_and_b32_e32 v12, 0xffff0000, v63
	v_mul_f32_e32 v13, 0xbfb8aa3b, v12
	v_exp_f32_e32 v13, v13
	v_mul_f32_e32 v9, v11, v9
	v_mul_f32_e32 v11, v35, v8
	v_add_f32_e32 v13, 1.0, v13
	v_rcp_f32_e32 v13, v13
	s_nop 0
	v_mul_f32_e32 v12, v13, v12
	v_mul_f32_e32 v11, v12, v11
	v_cvt_pk_bf16_f32 v11, v9, v11
	global_store_dwordx2 v[48:49], v[10:11], off offset:32
	s_waitcnt vmcnt(7)
; DI unsigned pk2(float lo, float hi) { unsigned r; asm volatile("v_cvt_pk_bf16_f32 %0, %1, %2" : "=v"(r) : "v"(lo), "v"(hi)); return r; }
; DI float bflo(unsigned u) { return __uint_as_float(u << 16); }
; DI float bfhi(unsigned u) { return __uint_as_float(u & 0xffff0000u); }
; DI float silu_f(float x) { return x * __builtin_amdgcn_rcpf(1.0f + __expf(-x)); }
; DI void ret_out_unit(const Params& p, int hf, int bl, int c, int hd, unsigned char* shm, int tid, bool dry = false) {
;     ...
; #pragma unroll
;   for (int n = 0; n < 8; ++n) {
;     const uint2 gv = gv8[n];
;     uint2 w;
;     w.x = pk2(o1[n][0] * rinv * silu_f(bflo(gv.x)), o1[n][1] * rinv * silu_f(bfhi(gv.x)));
;     w.y = pk2(o1[n][2] * rinv * silu_f(bflo(gv.y)), o1[n][3] * rinv * silu_f(bfhi(gv.y)));
;     if (!dry || rinv == 1.2345e-30f) *(uint2*)(gp + 16 * n) = w;
;   }
;   __syncthreads();
	v_lshlrev_b32_e32 v10, 16, v60
	v_mul_f32_e32 v11, 0xbfb8aa3b, v10
	v_exp_f32_e32 v11, v11
	v_mul_f32_e32 v9, v28, v8
	v_add_f32_e32 v11, 1.0, v11
	v_rcp_f32_e32 v11, v11
	s_nop 0
	v_mul_f32_e32 v10, v11, v10
	v_and_b32_e32 v11, 0xffff0000, v60
	v_mul_f32_e32 v12, 0xbfb8aa3b, v11
	v_exp_f32_e32 v12, v12
	v_mul_f32_e32 v9, v10, v9
	v_mul_f32_e32 v10, v29, v8
	v_add_f32_e32 v12, 1.0, v12
	v_rcp_f32_e32 v12, v12
	s_nop 0
	v_mul_f32_e32 v11, v12, v11
	v_mul_f32_e32 v10, v11, v10
	v_lshlrev_b32_e32 v11, 16, v61
	v_mul_f32_e32 v12, 0xbfb8aa3b, v11
	v_exp_f32_e32 v12, v12
	v_cvt_pk_bf16_f32 v10, v9, v10
	v_mul_f32_e32 v9, v30, v8
	v_add_f32_e32 v12, 1.0, v12
	v_rcp_f32_e32 v12, v12
	s_nop 0
	v_mul_f32_e32 v11, v12, v11
	v_and_b32_e32 v12, 0xffff0000, v61
	v_mul_f32_e32 v13, 0xbfb8aa3b, v12
	v_exp_f32_e32 v13, v13
	v_mul_f32_e32 v9, v11, v9
	v_mul_f32_e32 v11, v31, v8
	v_add_f32_e32 v13, 1.0, v13
	v_rcp_f32_e32 v13, v13
	s_nop 0
	v_mul_f32_e32 v12, v13, v12
	v_mul_f32_e32 v11, v12, v11
	v_cvt_pk_bf16_f32 v11, v9, v11
	global_store_dwordx2 v[48:49], v[10:11], off offset:64
	s_waitcnt vmcnt(7)
	v_lshlrev_b32_e32 v10, 16, v58
	v_mul_f32_e32 v11, 0xbfb8aa3b, v10
	v_exp_f32_e32 v11, v11
	v_mul_f32_e32 v9, v24, v8
	v_add_f32_e32 v11, 1.0, v11
	v_rcp_f32_e32 v11, v11
	s_nop 0
	v_mul_f32_e32 v10, v11, v10
	v_and_b32_e32 v11, 0xffff0000, v58
	v_mul_f32_e32 v12, 0xbfb8aa3b, v11
	v_exp_f32_e32 v12, v12
	v_mul_f32_e32 v9, v10, v9
	v_mul_f32_e32 v10, v25, v8
	v_add_f32_e32 v12, 1.0, v12
	v_rcp_f32_e32 v12, v12
	s_nop 0
	v_mul_f32_e32 v11, v12, v11
	v_mul_f32_e32 v10, v11, v10
	v_lshlrev_b32_e32 v11, 16, v59
	v_mul_f32_e32 v12, 0xbfb8aa3b, v11
	v_exp_f32_e32 v12, v12
	v_cvt_pk_bf16_f32 v10, v9, v10
	v_mul_f32_e32 v9, v26, v8
	v_add_f32_e32 v12, 1.0, v12
	v_rcp_f32_e32 v12, v12
	s_nop 0
	v_mul_f32_e32 v11, v12, v11
	v_and_b32_e32 v12, 0xffff0000, v59
	v_mul_f32_e32 v13, 0xbfb8aa3b, v12
	v_exp_f32_e32 v13, v13
	v_mul_f32_e32 v9, v11, v9
	v_mul_f32_e32 v11, v27, v8
	v_add_f32_e32 v13, 1.0, v13
	v_rcp_f32_e32 v13, v13
	s_nop 0
	v_mul_f32_e32 v12, v13, v12
	v_mul_f32_e32 v11, v12, v11
	v_cvt_pk_bf16_f32 v11, v9, v11
	global_store_dwordx2 v[48:49], v[10:11], off offset:96
	s_waitcnt vmcnt(7)
	v_lshlrev_b32_e32 v10, 16, v56
	v_mul_f32_e32 v11, 0xbfb8aa3b, v10
	v_exp_f32_e32 v11, v11
	v_mul_f32_e32 v9, v20, v8
	v_add_f32_e32 v11, 1.0, v11
	v_rcp_f32_e32 v11, v11
	s_nop 0
	v_mul_f32_e32 v10, v11, v10
	v_and_b32_e32 v11, 0xffff0000, v56
	v_mul_f32_e32 v12, 0xbfb8aa3b, v11
	v_exp_f32_e32 v12, v12
	v_mul_f32_e32 v9, v10, v9
	v_mul_f32_e32 v10, v21, v8
	v_add_f32_e32 v12, 1.0, v12
	v_rcp_f32_e32 v12, v12
	s_nop 0
	v_mul_f32_e32 v11, v12, v11
	v_mul_f32_e32 v10, v11, v10
	v_lshlrev_b32_e32 v11, 16, v57
	v_mul_f32_e32 v12, 0xbfb8aa3b, v11
	v_exp_f32_e32 v12, v12
	v_cvt_pk_bf16_f32 v10, v9, v10
	v_mul_f32_e32 v9, v22, v8
	v_add_f32_e32 v12, 1.0, v12
	v_rcp_f32_e32 v12, v12
	s_nop 0
	v_mul_f32_e32 v11, v12, v11
	v_and_b32_e32 v12, 0xffff0000, v57
	v_mul_f32_e32 v13, 0xbfb8aa3b, v12
	v_exp_f32_e32 v13, v13
	v_mul_f32_e32 v9, v11, v9
	v_mul_f32_e32 v11, v23, v8
	v_add_f32_e32 v13, 1.0, v13
	v_rcp_f32_e32 v13, v13
	s_nop 0
	v_mul_f32_e32 v12, v13, v12
	v_mul_f32_e32 v11, v12, v11
	v_cvt_pk_bf16_f32 v11, v9, v11
	global_store_dwordx2 v[48:49], v[10:11], off offset:128
	s_waitcnt vmcnt(7)
	v_lshlrev_b32_e32 v10, 16, v54
	v_mul_f32_e32 v11, 0xbfb8aa3b, v10
	v_exp_f32_e32 v11, v11
	v_mul_f32_e32 v9, v16, v8
	v_add_f32_e32 v11, 1.0, v11
	v_rcp_f32_e32 v11, v11
	s_nop 0
	v_mul_f32_e32 v10, v11, v10
	v_and_b32_e32 v11, 0xffff0000, v54
	v_mul_f32_e32 v12, 0xbfb8aa3b, v11
	v_exp_f32_e32 v12, v12
	v_mul_f32_e32 v9, v10, v9
	v_mul_f32_e32 v10, v17, v8
	v_add_f32_e32 v12, 1.0, v12
	v_rcp_f32_e32 v12, v12
	s_nop 0
	v_mul_f32_e32 v11, v12, v11
	v_mul_f32_e32 v10, v11, v10
	v_lshlrev_b32_e32 v11, 16, v55
	v_mul_f32_e32 v12, 0xbfb8aa3b, v11
	v_exp_f32_e32 v12, v12
	v_cvt_pk_bf16_f32 v10, v9, v10
	v_mul_f32_e32 v9, v18, v8
	v_add_f32_e32 v12, 1.0, v12
	v_rcp_f32_e32 v12, v12
	s_nop 0
	v_mul_f32_e32 v11, v12, v11
	v_and_b32_e32 v12, 0xffff0000, v55
	v_mul_f32_e32 v13, 0xbfb8aa3b, v12
	v_exp_f32_e32 v13, v13
	v_mul_f32_e32 v9, v11, v9
	v_mul_f32_e32 v11, v19, v8
	v_add_f32_e32 v13, 1.0, v13
	v_rcp_f32_e32 v13, v13
	s_nop 0
	v_mul_f32_e32 v12, v13, v12
	v_mul_f32_e32 v11, v12, v11
	v_cvt_pk_bf16_f32 v11, v9, v11
	s_waitcnt vmcnt(6)
	v_lshlrev_b32_e32 v9, 16, v52
	global_store_dwordx2 v[48:49], v[10:11], off offset:160
	v_mul_f32_e32 v10, 0xbfb8aa3b, v9
	v_exp_f32_e32 v10, v10
	s_nop 0
	v_add_f32_e32 v10, 1.0, v10
	v_rcp_f32_e32 v10, v10
	s_nop 0
	v_mul_f32_e32 v9, v10, v9
	v_mul_f32_e32 v6, v9, v6
	v_and_b32_e32 v9, 0xffff0000, v52
	v_mul_f32_e32 v10, 0xbfb8aa3b, v9
	v_exp_f32_e32 v10, v10
	s_nop 0
	v_add_f32_e32 v10, 1.0, v10
	v_rcp_f32_e32 v10, v10
	s_nop 0
	v_mul_f32_e32 v9, v10, v9
	v_mul_f32_e32 v7, v9, v7
	v_cvt_pk_bf16_f32 v6, v6, v7
	v_lshlrev_b32_e32 v7, 16, v53
	v_mul_f32_e32 v9, 0xbfb8aa3b, v7
	v_exp_f32_e32 v9, v9
	s_nop 0
	v_add_f32_e32 v9, 1.0, v9
	v_rcp_f32_e32 v9, v9
	s_nop 0
	v_mul_f32_e32 v7, v9, v7
	v_mul_f32_e32 v4, v7, v4
	v_and_b32_e32 v7, 0xffff0000, v53
	v_mul_f32_e32 v9, 0xbfb8aa3b, v7
	v_exp_f32_e32 v9, v9
	s_nop 0
	v_add_f32_e32 v9, 1.0, v9
	v_rcp_f32_e32 v9, v9
	s_nop 0
	v_mul_f32_e32 v7, v9, v7
	v_mul_f32_e32 v5, v7, v5
	v_cvt_pk_bf16_f32 v7, v4, v5
	s_waitcnt vmcnt(6)
	v_lshlrev_b32_e32 v4, 16, v50
	v_mul_f32_e32 v5, 0xbfb8aa3b, v4
	v_exp_f32_e32 v5, v5
	global_store_dwordx2 v[48:49], v[6:7], off offset:192
	v_add_f32_e32 v5, 1.0, v5
	v_rcp_f32_e32 v5, v5
	s_nop 0
	v_mul_f32_e32 v4, v5, v4
	v_mul_f32_e32 v2, v4, v2
	v_and_b32_e32 v4, 0xffff0000, v50
	v_mul_f32_e32 v5, 0xbfb8aa3b, v4
	v_exp_f32_e32 v5, v5
	s_nop 0
	v_add_f32_e32 v5, 1.0, v5
	v_rcp_f32_e32 v5, v5
	s_nop 0
	v_mul_f32_e32 v4, v5, v4
	v_mul_f32_e32 v3, v4, v3
	v_cvt_pk_bf16_f32 v2, v2, v3
	v_lshlrev_b32_e32 v3, 16, v51
	v_mul_f32_e32 v4, 0xbfb8aa3b, v3
	v_exp_f32_e32 v4, v4
	s_nop 0
	v_add_f32_e32 v4, 1.0, v4
	v_rcp_f32_e32 v4, v4
	s_nop 0
	v_mul_f32_e32 v3, v4, v3
	v_mul_f32_e32 v0, v3, v0
	v_and_b32_e32 v3, 0xffff0000, v51
	v_mul_f32_e32 v4, 0xbfb8aa3b, v3
	v_exp_f32_e32 v4, v4
	s_nop 0
	v_add_f32_e32 v4, 1.0, v4
	v_rcp_f32_e32 v4, v4
	s_nop 0
	v_mul_f32_e32 v3, v4, v3
	v_mul_f32_e32 v1, v3, v1
	v_cvt_pk_bf16_f32 v3, v0, v1
	global_store_dwordx2 v[48:49], v[2:3], off offset:224
	s_barrier
